# GEMM compute segments: removed the redundant s_waitcnt lgkmcnt(0) after the barrier (asm lgkmcnt(0) before the barrier already drains; no LDS/SMEM op between)
# baseline (speedup 1.0000x reference)
; #define PG8_STAGE(bufoff, gbase, voff) do { _Pragma("unroll") for (int _i = 0; _i < 2; ++_i) \
;         __builtin_amdgcn_global_load_lds((const unsigned*)((const char*)(gbase) + (voff)[_i]), (PG8_LAS unsigned*)(lds + (bufoff) + ldsw + _i * 8192), 16, 0, 0); } while (0)
; #define PG8_LDA(dst, b, h) do { _Pragma("unroll") for (int m = 0; m < 4; ++m) _Pragma("unroll") for (int k = 0; k < 2; ++k) dst[m][k] = *(const PG8_LAS bf16x8*)(lds + PG8_SA(b, h) + aoff + m * 2048 + k * 1024); } while (0)
; #define PG8_LDB(dst, b, h) do { _Pragma("unroll") for (int n = 0; n < 2; ++n) _Pragma("unroll") for (int k = 0; k < 2; ++k) dst[n][k] = *(const PG8_LAS bf16x8*)(lds + PG8_SB(b, h) + boff + n * 2048 + k * 1024); } while (0)
; #define PG8_MMA(ai, bj, At, Bt) do { __builtin_amdgcn_s_setprio(1); _Pragma("unroll") for (int m = 0; m < 4; ++m) _Pragma("unroll") for (int n = 0; n < 2; ++n) _Pragma("unroll") for (int k = 0; k < 2; ++k) \
;         acc[ai][bj][m][n] = __builtin_amdgcn_mfma_f32_16x16x32_bf16(Bt[n][k], At[m][k], acc[ai][bj][m][n], 0, 0, 0); __builtin_amdgcn_s_setprio(0); } while (0)
; #define PG8_WAIT_V(n) asm volatile("s_waitcnt vmcnt(" #n ")" ::: "memory")
; #define PG8_WAIT_L(n) asm volatile("s_waitcnt lgkmcnt(" #n ")" ::: "memory")
; template <class Epi, class Sched, bool ALIGN_EPI = false, bool SP2 = false>
; __device__ __forceinline__ void gemm_phase(PG8_LAS unsigned char* lds, const Gemm g, const Sched& S, const Epi& E) {
;     ...
;             const bool last = (t == nt - 2);
;             const char* a1 = cA + (size_t)(t + 1) * kstep;
;             const char* a2 = last ? nA : cA + (size_t)(t + 2) * kstep; const char* b2 = last ? nB : cB + (size_t)(t + 2) * kstep;
;             const char* a3 = a2 + kstep; const char* b3 = b2 + kstep;
;             if (last && has_next) S.a_ready(nxt);
;             if constexpr (SP2) {
;             PG8_LDB(B0, 0, 0); PG8_LDB(B1, 0, 1); PG8_SCHED; PG8_LDA(At, 0, 0); PG8_STAGE(PG8_SA(1, 1), a1 + hstep, voffA);
;             PG8_WAIT_V(8); PG8_WAIT_L(0); PG8_BAR; PG8_MMA(0, 0, At, B0); PG8_MMA(0, 1, At, B1); PG8_BAR; PG8_SCHED;
;             PG8_LDA(At, 0, 1); PG8_STAGE(PG8_SB(0, 0), b2, voffB); PG8_STAGE(PG8_SB(0, 1), b2 + hstep, voffB); PG8_STAGE(PG8_SA(0, 0), a2, voffA);
;             PG8_WAIT_V(8); PG8_WAIT_L(0); PG8_BAR; PG8_MMA(1, 0, At, B0); PG8_MMA(1, 1, At, B1); PG8_BAR; PG8_SCHED;
.LBB0_25:
	s_add_i32 s88, 0, 0x10000
	s_add_i32 s90, 0, 0x14000
	ds_read_b128 v[142:145], v200
	ds_read_b128 v[146:149], v200 offset:1024
	ds_read_b128 v[150:153], v200 offset:2048
	ds_read_b128 v[154:157], v200 offset:3072
	ds_read_b128 v[164:167], v200 offset:16384
	ds_read_b128 v[168:171], v200 offset:17408
	ds_read_b128 v[172:175], v200 offset:18432
	ds_read_b128 v[176:179], v200 offset:19456
	s_add_i32 m0, s29, 0xc000
	ds_read_b128 v[180:183], v141
	ds_read_b128 v[184:187], v141 offset:1024
	ds_read_b128 v[188:191], v141 offset:2048
	ds_read_b128 v[192:195], v141 offset:3072
	ds_read_b128 v[196:199], v141 offset:4096
	ds_read_b128 v[222:225], v141 offset:5120
	ds_read_b128 v[226:229], v141 offset:6144
	ds_read_b128 v[230:233], v141 offset:7168
	global_load_lds_dwordx4 v134, s[80:81]
	s_add_i32 m0, s29, 0xe000
	s_nop 0
	global_load_lds_dwordx4 v136, s[80:81]
	s_add_u32 s4, s80, 0xfff80080
	s_addc_u32 s5, s81, -1
	s_cmp_eq_u32 s87, 28
	s_cselect_b32 s53, s55, s5
	s_cselect_b32 s52, s83, s4
	s_cselect_b32 s5, s73, s86
	s_cselect_b32 s4, s84, s85
	s_waitcnt vmcnt(8)
	s_waitcnt lgkmcnt(0)
	s_barrier
	s_setprio 1
	v_mfma_f32_16x16x32_bf16 v[124:127], v[142:145], v[180:183], v[124:127]
	v_mfma_f32_16x16x32_bf16 v[120:123], v[150:153], v[180:183], v[120:123]
	v_mfma_f32_16x16x32_bf16 v[116:119], v[142:145], v[188:191], v[116:119]
	v_mfma_f32_16x16x32_bf16 v[112:115], v[150:153], v[188:191], v[112:115]
	v_mfma_f32_16x16x32_bf16 v[100:103], v[142:145], v[196:199], v[100:103]
	v_mfma_f32_16x16x32_bf16 v[96:99], v[150:153], v[196:199], v[96:99]
	v_mfma_f32_16x16x32_bf16 v[84:87], v[142:145], v[226:229], v[84:87]
	v_mfma_f32_16x16x32_bf16 v[80:83], v[150:153], v[226:229], v[80:83]
	v_mfma_f32_16x16x32_bf16 v[124:127], v[146:149], v[184:187], v[124:127]
	v_mfma_f32_16x16x32_bf16 v[120:123], v[154:157], v[184:187], v[120:123]
	v_mfma_f32_16x16x32_bf16 v[116:119], v[146:149], v[192:195], v[116:119]
	v_mfma_f32_16x16x32_bf16 v[112:115], v[154:157], v[192:195], v[112:115]
	v_mfma_f32_16x16x32_bf16 v[100:103], v[146:149], v[222:225], v[100:103]
	v_mfma_f32_16x16x32_bf16 v[96:99], v[154:157], v[222:225], v[96:99]
	v_mfma_f32_16x16x32_bf16 v[84:87], v[146:149], v[230:233], v[84:87]
	v_mfma_f32_16x16x32_bf16 v[80:83], v[154:157], v[230:233], v[80:83]
	v_mfma_f32_16x16x32_bf16 v[108:111], v[164:167], v[180:183], v[108:111]
	v_mfma_f32_16x16x32_bf16 v[104:107], v[172:175], v[180:183], v[104:107]
	v_mfma_f32_16x16x32_bf16 v[92:95], v[164:167], v[188:191], v[92:95]
	v_mfma_f32_16x16x32_bf16 v[88:91], v[172:175], v[188:191], v[88:91]
	v_mfma_f32_16x16x32_bf16 v[76:79], v[164:167], v[196:199], v[76:79]
	v_mfma_f32_16x16x32_bf16 v[72:75], v[172:175], v[196:199], v[72:75]
	v_mfma_f32_16x16x32_bf16 v[68:71], v[164:167], v[226:229], v[68:71]
	v_mfma_f32_16x16x32_bf16 v[64:67], v[172:175], v[226:229], v[64:67]
	v_mfma_f32_16x16x32_bf16 v[108:111], v[168:171], v[184:187], v[108:111]
	v_mfma_f32_16x16x32_bf16 v[104:107], v[176:179], v[184:187], v[104:107]
	v_mfma_f32_16x16x32_bf16 v[92:95], v[168:171], v[192:195], v[92:95]
	v_mfma_f32_16x16x32_bf16 v[88:91], v[176:179], v[192:195], v[88:91]
	v_mfma_f32_16x16x32_bf16 v[76:79], v[168:171], v[222:225], v[76:79]
	v_mfma_f32_16x16x32_bf16 v[72:75], v[176:179], v[222:225], v[72:75]
	v_mfma_f32_16x16x32_bf16 v[68:71], v[168:171], v[230:233], v[68:71]
	v_mfma_f32_16x16x32_bf16 v[64:67], v[176:179], v[230:233], v[64:67]
	s_setprio 0
	s_barrier
	s_add_i32 s88, s88, s28
	s_mov_b32 m0, s88
	ds_read_b128 v[180:183], v141 offset:16384
	ds_read_b128 v[184:187], v141 offset:17408
	ds_read_b128 v[188:191], v141 offset:18432
	ds_read_b128 v[192:195], v141 offset:19456
	ds_read_b128 v[196:199], v141 offset:20480
	ds_read_b128 v[222:225], v141 offset:21504
	ds_read_b128 v[226:229], v141 offset:22528
	ds_read_b128 v[230:233], v141 offset:23552
	global_load_lds_dwordx4 v160, s[4:5]
	s_add_i32 m0, s88, 0x2000
	s_add_u32 s88, s4, 0x80000
	s_addc_u32 s89, s5, 0
	s_add_i32 s90, s90, s28
	global_load_lds_dwordx4 v128, s[4:5]
	s_mov_b32 m0, s90
	s_nop 0
	global_load_lds_dwordx4 v160, s[88:89]
	s_add_i32 m0, s90, 0x2000
	s_nop 0
	global_load_lds_dwordx4 v128, s[88:89]
	s_mov_b32 m0, s29
	s_nop 0
	global_load_lds_dwordx4 v132, s[52:53]
	s_mov_b32 m0, s45
	s_nop 0
	global_load_lds_dwordx4 v130, s[52:53]
	s_add_u32 s98, s52, 0x80
	s_addc_u32 s99, s53, 0
	s_waitcnt vmcnt(8)
	s_waitcnt lgkmcnt(0)
	s_barrier
	s_setprio 1
	v_mfma_f32_16x16x32_bf16 v[60:63], v[142:145], v[180:183], v[60:63]
	v_mfma_f32_16x16x32_bf16 v[56:59], v[150:153], v[180:183], v[56:59]
	v_mfma_f32_16x16x32_bf16 v[52:55], v[142:145], v[188:191], v[52:55]
	v_mfma_f32_16x16x32_bf16 v[48:51], v[150:153], v[188:191], v[48:51]
	v_mfma_f32_16x16x32_bf16 v[36:39], v[142:145], v[196:199], v[36:39]
	v_mfma_f32_16x16x32_bf16 v[32:35], v[150:153], v[196:199], v[32:35]
	v_mfma_f32_16x16x32_bf16 v[20:23], v[142:145], v[226:229], v[20:23]
	v_mfma_f32_16x16x32_bf16 v[16:19], v[150:153], v[226:229], v[16:19]
	v_mfma_f32_16x16x32_bf16 v[60:63], v[146:149], v[184:187], v[60:63]
	v_mfma_f32_16x16x32_bf16 v[56:59], v[154:157], v[184:187], v[56:59]
	v_mfma_f32_16x16x32_bf16 v[52:55], v[146:149], v[192:195], v[52:55]
	v_mfma_f32_16x16x32_bf16 v[48:51], v[154:157], v[192:195], v[48:51]
	v_mfma_f32_16x16x32_bf16 v[36:39], v[146:149], v[222:225], v[36:39]
	v_mfma_f32_16x16x32_bf16 v[32:35], v[154:157], v[222:225], v[32:35]
	v_mfma_f32_16x16x32_bf16 v[20:23], v[146:149], v[230:233], v[20:23]
	v_mfma_f32_16x16x32_bf16 v[16:19], v[154:157], v[230:233], v[16:19]
	v_mfma_f32_16x16x32_bf16 v[44:47], v[164:167], v[180:183], v[44:47]
	v_mfma_f32_16x16x32_bf16 v[40:43], v[172:175], v[180:183], v[40:43]
	v_mfma_f32_16x16x32_bf16 v[28:31], v[164:167], v[188:191], v[28:31]
	v_mfma_f32_16x16x32_bf16 v[24:27], v[172:175], v[188:191], v[24:27]
	v_mfma_f32_16x16x32_bf16 v[12:15], v[164:167], v[196:199], v[12:15]
	v_mfma_f32_16x16x32_bf16 v[8:11], v[172:175], v[196:199], v[8:11]
	v_mfma_f32_16x16x32_bf16 v[4:7], v[164:167], v[226:229], v[4:7]
	v_mfma_f32_16x16x32_bf16 v[0:3], v[172:175], v[226:229], v[0:3]
	v_mfma_f32_16x16x32_bf16 v[44:47], v[168:171], v[184:187], v[44:47]
	v_mfma_f32_16x16x32_bf16 v[40:43], v[176:179], v[184:187], v[40:43]
	v_mfma_f32_16x16x32_bf16 v[28:31], v[168:171], v[192:195], v[28:31]
	v_mfma_f32_16x16x32_bf16 v[24:27], v[176:179], v[192:195], v[24:27]
	v_mfma_f32_16x16x32_bf16 v[12:15], v[168:171], v[222:225], v[12:15]
	v_mfma_f32_16x16x32_bf16 v[8:11], v[176:179], v[222:225], v[8:11]
	v_mfma_f32_16x16x32_bf16 v[4:7], v[168:171], v[230:233], v[4:7]
	v_mfma_f32_16x16x32_bf16 v[0:3], v[176:179], v[230:233], v[0:3]
	s_setprio 0
	s_barrier
; #define PG8_STAGE(bufoff, gbase, voff) do { _Pragma("unroll") for (int _i = 0; _i < 2; ++_i) \
;         __builtin_amdgcn_global_load_lds((const unsigned*)((const char*)(gbase) + (voff)[_i]), (PG8_LAS unsigned*)(lds + (bufoff) + ldsw + _i * 8192), 16, 0, 0); } while (0)
; #define PG8_LDA(dst, b, h) do { _Pragma("unroll") for (int m = 0; m < 4; ++m) _Pragma("unroll") for (int k = 0; k < 2; ++k) dst[m][k] = *(const PG8_LAS bf16x8*)(lds + PG8_SA(b, h) + aoff + m * 2048 + k * 1024); } while (0)
; #define PG8_LDB(dst, b, h) do { _Pragma("unroll") for (int n = 0; n < 2; ++n) _Pragma("unroll") for (int k = 0; k < 2; ++k) dst[n][k] = *(const PG8_LAS bf16x8*)(lds + PG8_SB(b, h) + boff + n * 2048 + k * 1024); } while (0)
; #define PG8_MMA(ai, bj, At, Bt) do { __builtin_amdgcn_s_setprio(1); _Pragma("unroll") for (int m = 0; m < 4; ++m) _Pragma("unroll") for (int n = 0; n < 2; ++n) _Pragma("unroll") for (int k = 0; k < 2; ++k) \
;         acc[ai][bj][m][n] = __builtin_amdgcn_mfma_f32_16x16x32_bf16(Bt[n][k], At[m][k], acc[ai][bj][m][n], 0, 0, 0); __builtin_amdgcn_s_setprio(0); } while (0)
; #define PG8_WAIT_V(n) asm volatile("s_waitcnt vmcnt(" #n ")" ::: "memory")
; #define PG8_WAIT_L(n) asm volatile("s_waitcnt lgkmcnt(" #n ")" ::: "memory")
; #define PG8_BAR __builtin_amdgcn_s_barrier()
; #define PG8_SCHED __builtin_amdgcn_sched_barrier(0)
; template <class Epi, class Sched, bool ALIGN_EPI = false, bool SP2 = false>
; __device__ __forceinline__ void gemm_phase(PG8_LAS unsigned char* lds, const Gemm g, const Sched& S, const Epi& E) {
;     ...
;             PG8_LDB(B0, 1, 0); PG8_LDB(B1, 1, 1); PG8_SCHED; PG8_LDA(At, 1, 0); PG8_STAGE(PG8_SA(0, 1), a2 + hstep, voffA);
;             PG8_WAIT_V(8); PG8_WAIT_L(0); PG8_BAR; PG8_MMA(0, 0, At, B0); PG8_MMA(0, 1, At, B1); PG8_BAR; PG8_SCHED;
;             PG8_LDA(At, 1, 1); PG8_STAGE(PG8_SB(1, 0), b3, voffB); PG8_STAGE(PG8_SB(1, 1), b3 + hstep, voffB); PG8_STAGE(PG8_SA(1, 0), a3, voffA);
;             PG8_WAIT_V(8); PG8_WAIT_L(0); PG8_BAR; PG8_MMA(1, 0, At, B0); PG8_MMA(1, 1, At, B1); PG8_BAR; PG8_SCHED;
;     ...
;         if constexpr (ALIGN_EPI) { if (wr == 0) PG8_BAR; }
	s_add_i32 s88, 0, 0x18000
	s_add_i32 s89, 0, 0x1c000
	ds_read_b128 v[142:145], v200 offset:32768
	ds_read_b128 v[146:149], v200 offset:33792
	ds_read_b128 v[150:153], v200 offset:34816
	ds_read_b128 v[154:157], v200 offset:35840
	ds_read_b128 v[164:167], v200 offset:49152
	ds_read_b128 v[168:171], v200 offset:50176
	ds_read_b128 v[172:175], v200 offset:51200
	ds_read_b128 v[176:179], v200 offset:52224
	s_add_u32 s52, s52, 0x80000
	s_addc_u32 s53, s53, 0
	s_mov_b32 m0, s56
	ds_read_b128 v[180:183], v141 offset:32768
	ds_read_b128 v[184:187], v141 offset:33792
	ds_read_b128 v[188:191], v141 offset:34816
	ds_read_b128 v[192:195], v141 offset:35840
	ds_read_b128 v[196:199], v141 offset:36864
	ds_read_b128 v[222:225], v141 offset:37888
	ds_read_b128 v[226:229], v141 offset:38912
	ds_read_b128 v[230:233], v141 offset:39936
	global_load_lds_dwordx4 v132, s[52:53]
	s_mov_b32 m0, s57
	s_nop 0
	global_load_lds_dwordx4 v130, s[52:53]
	s_waitcnt vmcnt(8)
	s_waitcnt lgkmcnt(0)
	s_barrier
	s_setprio 1
	v_mfma_f32_16x16x32_bf16 v[124:127], v[142:145], v[180:183], v[124:127]
	v_mfma_f32_16x16x32_bf16 v[120:123], v[150:153], v[180:183], v[120:123]
	v_mfma_f32_16x16x32_bf16 v[116:119], v[142:145], v[188:191], v[116:119]
	v_mfma_f32_16x16x32_bf16 v[112:115], v[150:153], v[188:191], v[112:115]
	v_mfma_f32_16x16x32_bf16 v[100:103], v[142:145], v[196:199], v[100:103]
	v_mfma_f32_16x16x32_bf16 v[96:99], v[150:153], v[196:199], v[96:99]
	v_mfma_f32_16x16x32_bf16 v[84:87], v[142:145], v[226:229], v[84:87]
	v_mfma_f32_16x16x32_bf16 v[80:83], v[150:153], v[226:229], v[80:83]
	v_mfma_f32_16x16x32_bf16 v[124:127], v[146:149], v[184:187], v[124:127]
	v_mfma_f32_16x16x32_bf16 v[120:123], v[154:157], v[184:187], v[120:123]
	v_mfma_f32_16x16x32_bf16 v[116:119], v[146:149], v[192:195], v[116:119]
	v_mfma_f32_16x16x32_bf16 v[112:115], v[154:157], v[192:195], v[112:115]
	v_mfma_f32_16x16x32_bf16 v[100:103], v[146:149], v[222:225], v[100:103]
	v_mfma_f32_16x16x32_bf16 v[96:99], v[154:157], v[222:225], v[96:99]
	v_mfma_f32_16x16x32_bf16 v[84:87], v[146:149], v[230:233], v[84:87]
	v_mfma_f32_16x16x32_bf16 v[80:83], v[154:157], v[230:233], v[80:83]
	v_mfma_f32_16x16x32_bf16 v[108:111], v[164:167], v[180:183], v[108:111]
	v_mfma_f32_16x16x32_bf16 v[104:107], v[172:175], v[180:183], v[104:107]
	v_mfma_f32_16x16x32_bf16 v[92:95], v[164:167], v[188:191], v[92:95]
	v_mfma_f32_16x16x32_bf16 v[88:91], v[172:175], v[188:191], v[88:91]
	v_mfma_f32_16x16x32_bf16 v[76:79], v[164:167], v[196:199], v[76:79]
	v_mfma_f32_16x16x32_bf16 v[72:75], v[172:175], v[196:199], v[72:75]
	v_mfma_f32_16x16x32_bf16 v[68:71], v[164:167], v[226:229], v[68:71]
	v_mfma_f32_16x16x32_bf16 v[64:67], v[172:175], v[226:229], v[64:67]
	v_mfma_f32_16x16x32_bf16 v[108:111], v[168:171], v[184:187], v[108:111]
	v_mfma_f32_16x16x32_bf16 v[104:107], v[176:179], v[184:187], v[104:107]
	v_mfma_f32_16x16x32_bf16 v[92:95], v[168:171], v[192:195], v[92:95]
	v_mfma_f32_16x16x32_bf16 v[88:91], v[176:179], v[192:195], v[88:91]
	v_mfma_f32_16x16x32_bf16 v[76:79], v[168:171], v[222:225], v[76:79]
	v_mfma_f32_16x16x32_bf16 v[72:75], v[176:179], v[222:225], v[72:75]
	v_mfma_f32_16x16x32_bf16 v[68:71], v[168:171], v[230:233], v[68:71]
	v_mfma_f32_16x16x32_bf16 v[64:67], v[176:179], v[230:233], v[64:67]
	s_setprio 0
	s_barrier
	s_add_i32 s52, s88, s28
	s_mov_b32 m0, s52
	ds_read_b128 v[180:183], v141 offset:49152
	ds_read_b128 v[184:187], v141 offset:50176
	ds_read_b128 v[188:191], v141 offset:51200
	ds_read_b128 v[192:195], v141 offset:52224
	ds_read_b128 v[196:199], v141 offset:53248
	ds_read_b128 v[222:225], v141 offset:54272
	ds_read_b128 v[226:229], v141 offset:55296
	ds_read_b128 v[230:233], v141 offset:56320
	s_add_u32 s4, s4, 0x80
	s_addc_u32 s5, s5, 0
	global_load_lds_dwordx4 v160, s[4:5]
	s_add_i32 m0, s52, 0x2000
	s_add_i32 s52, s89, s28
	global_load_lds_dwordx4 v128, s[4:5]
	s_add_u32 s4, s4, 0x80000
	s_addc_u32 s5, s5, 0
	s_mov_b32 m0, s52
	s_nop 0
	global_load_lds_dwordx4 v160, s[4:5]
	s_add_i32 m0, s52, 0x2000
	s_nop 0
	global_load_lds_dwordx4 v128, s[4:5]
	s_mov_b32 m0, s24
	s_nop 0
	global_load_lds_dwordx4 v132, s[98:99]
	s_mov_b32 m0, s59
	s_nop 0
	global_load_lds_dwordx4 v130, s[98:99]
	s_waitcnt vmcnt(8)
	s_waitcnt lgkmcnt(0)
	s_barrier
	s_setprio 1
	v_mfma_f32_16x16x32_bf16 v[60:63], v[142:145], v[180:183], v[60:63]
	v_mfma_f32_16x16x32_bf16 v[56:59], v[150:153], v[180:183], v[56:59]
	v_mfma_f32_16x16x32_bf16 v[52:55], v[142:145], v[188:191], v[52:55]
	v_mfma_f32_16x16x32_bf16 v[48:51], v[150:153], v[188:191], v[48:51]
	v_mfma_f32_16x16x32_bf16 v[36:39], v[142:145], v[196:199], v[36:39]
	v_mfma_f32_16x16x32_bf16 v[32:35], v[150:153], v[196:199], v[32:35]
	v_mfma_f32_16x16x32_bf16 v[20:23], v[142:145], v[226:229], v[20:23]
	v_mfma_f32_16x16x32_bf16 v[16:19], v[150:153], v[226:229], v[16:19]
	v_mfma_f32_16x16x32_bf16 v[60:63], v[146:149], v[184:187], v[60:63]
	v_mfma_f32_16x16x32_bf16 v[56:59], v[154:157], v[184:187], v[56:59]
	v_mfma_f32_16x16x32_bf16 v[52:55], v[146:149], v[192:195], v[52:55]
	v_mfma_f32_16x16x32_bf16 v[48:51], v[154:157], v[192:195], v[48:51]
	v_mfma_f32_16x16x32_bf16 v[36:39], v[146:149], v[222:225], v[36:39]
	v_mfma_f32_16x16x32_bf16 v[32:35], v[154:157], v[222:225], v[32:35]
	v_mfma_f32_16x16x32_bf16 v[20:23], v[146:149], v[230:233], v[20:23]
	v_mfma_f32_16x16x32_bf16 v[16:19], v[154:157], v[230:233], v[16:19]
	v_mfma_f32_16x16x32_bf16 v[44:47], v[164:167], v[180:183], v[44:47]
	v_mfma_f32_16x16x32_bf16 v[40:43], v[172:175], v[180:183], v[40:43]
	v_mfma_f32_16x16x32_bf16 v[28:31], v[164:167], v[188:191], v[28:31]
	v_mfma_f32_16x16x32_bf16 v[24:27], v[172:175], v[188:191], v[24:27]
	v_mfma_f32_16x16x32_bf16 v[12:15], v[164:167], v[196:199], v[12:15]
	v_mfma_f32_16x16x32_bf16 v[8:11], v[172:175], v[196:199], v[8:11]
	v_mfma_f32_16x16x32_bf16 v[4:7], v[164:167], v[226:229], v[4:7]
	v_mfma_f32_16x16x32_bf16 v[0:3], v[172:175], v[226:229], v[0:3]
	v_mfma_f32_16x16x32_bf16 v[44:47], v[168:171], v[184:187], v[44:47]
	v_mfma_f32_16x16x32_bf16 v[40:43], v[176:179], v[184:187], v[40:43]
	v_mfma_f32_16x16x32_bf16 v[28:31], v[168:171], v[192:195], v[28:31]
	v_mfma_f32_16x16x32_bf16 v[24:27], v[176:179], v[192:195], v[24:27]
	v_mfma_f32_16x16x32_bf16 v[12:15], v[168:171], v[222:225], v[12:15]
	v_mfma_f32_16x16x32_bf16 v[8:11], v[176:179], v[222:225], v[8:11]
	v_mfma_f32_16x16x32_bf16 v[4:7], v[168:171], v[230:233], v[4:7]
	v_mfma_f32_16x16x32_bf16 v[0:3], v[176:179], v[230:233], v[0:3]
	s_setprio 0
	s_barrier
	s_add_i32 s87, s87, 2
	s_add_u32 s80, s80, 0x100
	s_addc_u32 s81, s81, 0
	s_add_u32 s85, s85, 0x100
	s_addc_u32 s86, s86, 0
	s_cmp_gt_u32 s87, 29
	s_cbranch_scc0 .LBB0_25
	s_and_b64 vcc, exec, s[42:43]
	s_cbranch_vccz .LBB0_28
	s_barrier

; #define PG8_STAGE(bufoff, gbase, voff) do { _Pragma("unroll") for (int _i = 0; _i < 2; ++_i) \
;         __builtin_amdgcn_global_load_lds((const unsigned*)((const char*)(gbase) + (voff)[_i]), (PG8_LAS unsigned*)(lds + (bufoff) + ldsw + _i * 8192), 16, 0, 0); } while (0)
; #define PG8_LDA(dst, b, h) do { _Pragma("unroll") for (int m = 0; m < 4; ++m) _Pragma("unroll") for (int k = 0; k < 2; ++k) dst[m][k] = *(const PG8_LAS bf16x8*)(lds + PG8_SA(b, h) + aoff + m * 2048 + k * 1024); } while (0)
; #define PG8_LDB(dst, b, h) do { _Pragma("unroll") for (int n = 0; n < 2; ++n) _Pragma("unroll") for (int k = 0; k < 2; ++k) dst[n][k] = *(const PG8_LAS bf16x8*)(lds + PG8_SB(b, h) + boff + n * 2048 + k * 1024); } while (0)
; #define PG8_MMA(ai, bj, At, Bt) do { __builtin_amdgcn_s_setprio(1); _Pragma("unroll") for (int m = 0; m < 4; ++m) _Pragma("unroll") for (int n = 0; n < 2; ++n) _Pragma("unroll") for (int k = 0; k < 2; ++k) \
;         acc[ai][bj][m][n] = __builtin_amdgcn_mfma_f32_16x16x32_bf16(Bt[n][k], At[m][k], acc[ai][bj][m][n], 0, 0, 0); __builtin_amdgcn_s_setprio(0); } while (0)
; #define PG8_WAIT_V(n) asm volatile("s_waitcnt vmcnt(" #n ")" ::: "memory")
; #define PG8_WAIT_L(n) asm volatile("s_waitcnt lgkmcnt(" #n ")" ::: "memory")
; template <class Epi, class Sched, bool ALIGN_EPI = false, bool SP2 = false>
; __device__ __forceinline__ void gemm_phase(PG8_LAS unsigned char* lds, const Gemm g, const Sched& S, const Epi& E) {
;     ...
;             const bool last = (t == nt - 2);
;             const char* a1 = cA + (size_t)(t + 1) * kstep;
;             const char* a2 = last ? nA : cA + (size_t)(t + 2) * kstep; const char* b2 = last ? nB : cB + (size_t)(t + 2) * kstep;
;             const char* a3 = a2 + kstep; const char* b3 = b2 + kstep;
;             if (last && has_next) S.a_ready(nxt);
;             if constexpr (SP2) {
;             PG8_LDB(B0, 0, 0); PG8_LDB(B1, 0, 1); PG8_SCHED; PG8_LDA(At, 0, 0); PG8_STAGE(PG8_SA(1, 1), a1 + hstep, voffA);
;             PG8_WAIT_V(8); PG8_WAIT_L(0); PG8_BAR; PG8_MMA(0, 0, At, B0); PG8_MMA(0, 1, At, B1); PG8_BAR; PG8_SCHED;
;             PG8_LDA(At, 0, 1); PG8_STAGE(PG8_SB(0, 0), b2, voffB); PG8_STAGE(PG8_SB(0, 1), b2 + hstep, voffB); PG8_STAGE(PG8_SA(0, 0), a2, voffA);
;             PG8_WAIT_V(8); PG8_WAIT_L(0); PG8_BAR; PG8_MMA(1, 0, At, B0); PG8_MMA(1, 1, At, B1); PG8_BAR; PG8_SCHED;
.LBB0_52:
	s_add_i32 s84, 0, 0x10000
	s_add_i32 s85, 0, 0x14000
	ds_read_b128 v[142:145], v200
	ds_read_b128 v[146:149], v200 offset:1024
	ds_read_b128 v[150:153], v200 offset:2048
	ds_read_b128 v[154:157], v200 offset:3072
	ds_read_b128 v[164:167], v200 offset:16384
	ds_read_b128 v[168:171], v200 offset:17408
	ds_read_b128 v[172:175], v200 offset:18432
	ds_read_b128 v[176:179], v200 offset:19456
	s_add_i32 m0, s28, 0xc000
	ds_read_b128 v[180:183], v141
	ds_read_b128 v[184:187], v141 offset:1024
	ds_read_b128 v[188:191], v141 offset:2048
	ds_read_b128 v[192:195], v141 offset:3072
	ds_read_b128 v[196:199], v141 offset:4096
	ds_read_b128 v[222:225], v141 offset:5120
	ds_read_b128 v[226:229], v141 offset:6144
	ds_read_b128 v[230:233], v141 offset:7168
	global_load_lds_dwordx4 v134, s[72:73]
	s_add_i32 m0, s28, 0xe000
	s_nop 0
	global_load_lds_dwordx4 v136, s[72:73]
	s_add_u32 s4, s72, 0x100
	s_addc_u32 s5, s73, 0
	s_cmpk_eq_i32 s83, 0x54
	s_cselect_b32 s57, s45, s5
	s_cselect_b32 s56, s44, s4
	s_cselect_b32 s53, s55, s82
	s_cselect_b32 s52, s54, s81
	s_waitcnt vmcnt(8)
	s_waitcnt lgkmcnt(0)
	s_barrier
	s_setprio 1
	v_mfma_f32_16x16x32_bf16 v[124:127], v[142:145], v[180:183], v[124:127]
	v_mfma_f32_16x16x32_bf16 v[120:123], v[150:153], v[180:183], v[120:123]
	v_mfma_f32_16x16x32_bf16 v[116:119], v[142:145], v[188:191], v[116:119]
	v_mfma_f32_16x16x32_bf16 v[112:115], v[150:153], v[188:191], v[112:115]
	v_mfma_f32_16x16x32_bf16 v[100:103], v[142:145], v[196:199], v[100:103]
	v_mfma_f32_16x16x32_bf16 v[96:99], v[150:153], v[196:199], v[96:99]
	v_mfma_f32_16x16x32_bf16 v[84:87], v[142:145], v[226:229], v[84:87]
	v_mfma_f32_16x16x32_bf16 v[80:83], v[150:153], v[226:229], v[80:83]
	v_mfma_f32_16x16x32_bf16 v[124:127], v[146:149], v[184:187], v[124:127]
	v_mfma_f32_16x16x32_bf16 v[120:123], v[154:157], v[184:187], v[120:123]
	v_mfma_f32_16x16x32_bf16 v[116:119], v[146:149], v[192:195], v[116:119]
	v_mfma_f32_16x16x32_bf16 v[112:115], v[154:157], v[192:195], v[112:115]
	v_mfma_f32_16x16x32_bf16 v[100:103], v[146:149], v[222:225], v[100:103]
	v_mfma_f32_16x16x32_bf16 v[96:99], v[154:157], v[222:225], v[96:99]
	v_mfma_f32_16x16x32_bf16 v[84:87], v[146:149], v[230:233], v[84:87]
	v_mfma_f32_16x16x32_bf16 v[80:83], v[154:157], v[230:233], v[80:83]
	v_mfma_f32_16x16x32_bf16 v[108:111], v[164:167], v[180:183], v[108:111]
	v_mfma_f32_16x16x32_bf16 v[104:107], v[172:175], v[180:183], v[104:107]
	v_mfma_f32_16x16x32_bf16 v[92:95], v[164:167], v[188:191], v[92:95]
	v_mfma_f32_16x16x32_bf16 v[88:91], v[172:175], v[188:191], v[88:91]
	v_mfma_f32_16x16x32_bf16 v[76:79], v[164:167], v[196:199], v[76:79]
	v_mfma_f32_16x16x32_bf16 v[72:75], v[172:175], v[196:199], v[72:75]
	v_mfma_f32_16x16x32_bf16 v[68:71], v[164:167], v[226:229], v[68:71]
	v_mfma_f32_16x16x32_bf16 v[64:67], v[172:175], v[226:229], v[64:67]
	v_mfma_f32_16x16x32_bf16 v[108:111], v[168:171], v[184:187], v[108:111]
	v_mfma_f32_16x16x32_bf16 v[104:107], v[176:179], v[184:187], v[104:107]
	v_mfma_f32_16x16x32_bf16 v[92:95], v[168:171], v[192:195], v[92:95]
	v_mfma_f32_16x16x32_bf16 v[88:91], v[176:179], v[192:195], v[88:91]
	v_mfma_f32_16x16x32_bf16 v[76:79], v[168:171], v[222:225], v[76:79]
	v_mfma_f32_16x16x32_bf16 v[72:75], v[176:179], v[222:225], v[72:75]
	v_mfma_f32_16x16x32_bf16 v[68:71], v[168:171], v[230:233], v[68:71]
	v_mfma_f32_16x16x32_bf16 v[64:67], v[176:179], v[230:233], v[64:67]
	s_setprio 0
	s_barrier
	s_add_i32 s72, s84, s24
	s_mov_b32 m0, s72
	ds_read_b128 v[180:183], v141 offset:16384
	ds_read_b128 v[184:187], v141 offset:17408
	ds_read_b128 v[188:191], v141 offset:18432
	ds_read_b128 v[192:195], v141 offset:19456
	ds_read_b128 v[196:199], v141 offset:20480
	ds_read_b128 v[222:225], v141 offset:21504
	ds_read_b128 v[226:229], v141 offset:22528
	ds_read_b128 v[230:233], v141 offset:23552
	global_load_lds_dwordx4 v160, s[52:53]
	s_add_i32 m0, s72, 0x2000
	s_add_u32 s72, s52, 0x160000
	s_addc_u32 s73, s53, 0
	s_add_i32 s84, s85, s24
	global_load_lds_dwordx4 v128, s[52:53]
	s_mov_b32 m0, s84
	s_nop 0
	global_load_lds_dwordx4 v160, s[72:73]
	s_add_i32 m0, s84, 0x2000
	s_nop 0
	global_load_lds_dwordx4 v128, s[72:73]
	s_mov_b32 m0, s28
	s_nop 0
	global_load_lds_dwordx4 v132, s[56:57]
	s_mov_b32 m0, s29
	s_nop 0
	global_load_lds_dwordx4 v130, s[56:57]
	s_add_u32 s98, s56, 0x80
	s_addc_u32 s99, s57, 0
	s_waitcnt vmcnt(8)
	s_waitcnt lgkmcnt(0)
	s_barrier
	s_setprio 1
	v_mfma_f32_16x16x32_bf16 v[60:63], v[142:145], v[180:183], v[60:63]
	v_mfma_f32_16x16x32_bf16 v[56:59], v[150:153], v[180:183], v[56:59]
	v_mfma_f32_16x16x32_bf16 v[52:55], v[142:145], v[188:191], v[52:55]
	v_mfma_f32_16x16x32_bf16 v[48:51], v[150:153], v[188:191], v[48:51]
	v_mfma_f32_16x16x32_bf16 v[36:39], v[142:145], v[196:199], v[36:39]
	v_mfma_f32_16x16x32_bf16 v[32:35], v[150:153], v[196:199], v[32:35]
	v_mfma_f32_16x16x32_bf16 v[20:23], v[142:145], v[226:229], v[20:23]
	v_mfma_f32_16x16x32_bf16 v[16:19], v[150:153], v[226:229], v[16:19]
	v_mfma_f32_16x16x32_bf16 v[60:63], v[146:149], v[184:187], v[60:63]
	v_mfma_f32_16x16x32_bf16 v[56:59], v[154:157], v[184:187], v[56:59]
	v_mfma_f32_16x16x32_bf16 v[52:55], v[146:149], v[192:195], v[52:55]
	v_mfma_f32_16x16x32_bf16 v[48:51], v[154:157], v[192:195], v[48:51]
	v_mfma_f32_16x16x32_bf16 v[36:39], v[146:149], v[222:225], v[36:39]
	v_mfma_f32_16x16x32_bf16 v[32:35], v[154:157], v[222:225], v[32:35]
	v_mfma_f32_16x16x32_bf16 v[20:23], v[146:149], v[230:233], v[20:23]
	v_mfma_f32_16x16x32_bf16 v[16:19], v[154:157], v[230:233], v[16:19]
	v_mfma_f32_16x16x32_bf16 v[44:47], v[164:167], v[180:183], v[44:47]
	v_mfma_f32_16x16x32_bf16 v[40:43], v[172:175], v[180:183], v[40:43]
	v_mfma_f32_16x16x32_bf16 v[28:31], v[164:167], v[188:191], v[28:31]
	v_mfma_f32_16x16x32_bf16 v[24:27], v[172:175], v[188:191], v[24:27]
	v_mfma_f32_16x16x32_bf16 v[12:15], v[164:167], v[196:199], v[12:15]
	v_mfma_f32_16x16x32_bf16 v[8:11], v[172:175], v[196:199], v[8:11]
	v_mfma_f32_16x16x32_bf16 v[4:7], v[164:167], v[226:229], v[4:7]
	v_mfma_f32_16x16x32_bf16 v[0:3], v[172:175], v[226:229], v[0:3]
	v_mfma_f32_16x16x32_bf16 v[44:47], v[168:171], v[184:187], v[44:47]
	v_mfma_f32_16x16x32_bf16 v[40:43], v[176:179], v[184:187], v[40:43]
	v_mfma_f32_16x16x32_bf16 v[28:31], v[168:171], v[192:195], v[28:31]
	v_mfma_f32_16x16x32_bf16 v[24:27], v[176:179], v[192:195], v[24:27]
	v_mfma_f32_16x16x32_bf16 v[12:15], v[168:171], v[222:225], v[12:15]
	v_mfma_f32_16x16x32_bf16 v[8:11], v[176:179], v[222:225], v[8:11]
	v_mfma_f32_16x16x32_bf16 v[4:7], v[168:171], v[230:233], v[4:7]
	v_mfma_f32_16x16x32_bf16 v[0:3], v[176:179], v[230:233], v[0:3]
	s_setprio 0
	s_barrier
; #define PG8_STAGE(bufoff, gbase, voff) do { _Pragma("unroll") for (int _i = 0; _i < 2; ++_i) \
;         __builtin_amdgcn_global_load_lds((const unsigned*)((const char*)(gbase) + (voff)[_i]), (PG8_LAS unsigned*)(lds + (bufoff) + ldsw + _i * 8192), 16, 0, 0); } while (0)
; #define PG8_LDA(dst, b, h) do { _Pragma("unroll") for (int m = 0; m < 4; ++m) _Pragma("unroll") for (int k = 0; k < 2; ++k) dst[m][k] = *(const PG8_LAS bf16x8*)(lds + PG8_SA(b, h) + aoff + m * 2048 + k * 1024); } while (0)
; #define PG8_LDB(dst, b, h) do { _Pragma("unroll") for (int n = 0; n < 2; ++n) _Pragma("unroll") for (int k = 0; k < 2; ++k) dst[n][k] = *(const PG8_LAS bf16x8*)(lds + PG8_SB(b, h) + boff + n * 2048 + k * 1024); } while (0)
; #define PG8_MMA(ai, bj, At, Bt) do { __builtin_amdgcn_s_setprio(1); _Pragma("unroll") for (int m = 0; m < 4; ++m) _Pragma("unroll") for (int n = 0; n < 2; ++n) _Pragma("unroll") for (int k = 0; k < 2; ++k) \
;         acc[ai][bj][m][n] = __builtin_amdgcn_mfma_f32_16x16x32_bf16(Bt[n][k], At[m][k], acc[ai][bj][m][n], 0, 0, 0); __builtin_amdgcn_s_setprio(0); } while (0)
; #define PG8_WAIT_V(n) asm volatile("s_waitcnt vmcnt(" #n ")" ::: "memory")
; #define PG8_WAIT_L(n) asm volatile("s_waitcnt lgkmcnt(" #n ")" ::: "memory")
; #define PG8_BAR __builtin_amdgcn_s_barrier()
; #define PG8_SCHED __builtin_amdgcn_sched_barrier(0)
; template <class Epi, class Sched, bool ALIGN_EPI = false, bool SP2 = false>
; __device__ __forceinline__ void gemm_phase(PG8_LAS unsigned char* lds, const Gemm g, const Sched& S, const Epi& E) {
;     ...
;             PG8_LDB(B0, 1, 0); PG8_LDB(B1, 1, 1); PG8_SCHED; PG8_LDA(At, 1, 0); PG8_STAGE(PG8_SA(0, 1), a2 + hstep, voffA);
;             PG8_WAIT_V(8); PG8_WAIT_L(0); PG8_BAR; PG8_MMA(0, 0, At, B0); PG8_MMA(0, 1, At, B1); PG8_BAR; PG8_SCHED;
;             PG8_LDA(At, 1, 1); PG8_STAGE(PG8_SB(1, 0), b3, voffB); PG8_STAGE(PG8_SB(1, 1), b3 + hstep, voffB); PG8_STAGE(PG8_SA(1, 0), a3, voffA);
;             PG8_WAIT_V(8); PG8_WAIT_L(0); PG8_BAR; PG8_MMA(1, 0, At, B0); PG8_MMA(1, 1, At, B1); PG8_BAR; PG8_SCHED;
;     ...
;         if constexpr (ALIGN_EPI) { if (wr == 0) PG8_BAR; }
	s_add_i32 s72, 0, 0x18000
	s_add_i32 s73, 0, 0x1c000
	ds_read_b128 v[142:145], v200 offset:32768
	ds_read_b128 v[146:149], v200 offset:33792
	ds_read_b128 v[150:153], v200 offset:34816
	ds_read_b128 v[154:157], v200 offset:35840
	ds_read_b128 v[164:167], v200 offset:49152
	ds_read_b128 v[168:171], v200 offset:50176
	ds_read_b128 v[172:175], v200 offset:51200
	ds_read_b128 v[176:179], v200 offset:52224
	s_add_u32 s56, s56, 0x160000
	s_addc_u32 s57, s57, 0
	s_mov_b32 m0, s59
	ds_read_b128 v[180:183], v141 offset:32768
	ds_read_b128 v[184:187], v141 offset:33792
	ds_read_b128 v[188:191], v141 offset:34816
	ds_read_b128 v[192:195], v141 offset:35840
	ds_read_b128 v[196:199], v141 offset:36864
	ds_read_b128 v[222:225], v141 offset:37888
	ds_read_b128 v[226:229], v141 offset:38912
	ds_read_b128 v[230:233], v141 offset:39936
	global_load_lds_dwordx4 v132, s[56:57]
	s_mov_b32 m0, s63
	s_nop 0
	global_load_lds_dwordx4 v130, s[56:57]
	s_waitcnt vmcnt(8)
	s_waitcnt lgkmcnt(0)
	s_barrier
	s_setprio 1
	v_mfma_f32_16x16x32_bf16 v[124:127], v[142:145], v[180:183], v[124:127]
	v_mfma_f32_16x16x32_bf16 v[120:123], v[150:153], v[180:183], v[120:123]
	v_mfma_f32_16x16x32_bf16 v[116:119], v[142:145], v[188:191], v[116:119]
	v_mfma_f32_16x16x32_bf16 v[112:115], v[150:153], v[188:191], v[112:115]
	v_mfma_f32_16x16x32_bf16 v[100:103], v[142:145], v[196:199], v[100:103]
	v_mfma_f32_16x16x32_bf16 v[96:99], v[150:153], v[196:199], v[96:99]
	v_mfma_f32_16x16x32_bf16 v[84:87], v[142:145], v[226:229], v[84:87]
	v_mfma_f32_16x16x32_bf16 v[80:83], v[150:153], v[226:229], v[80:83]
	v_mfma_f32_16x16x32_bf16 v[124:127], v[146:149], v[184:187], v[124:127]
	v_mfma_f32_16x16x32_bf16 v[120:123], v[154:157], v[184:187], v[120:123]
	v_mfma_f32_16x16x32_bf16 v[116:119], v[146:149], v[192:195], v[116:119]
	v_mfma_f32_16x16x32_bf16 v[112:115], v[154:157], v[192:195], v[112:115]
	v_mfma_f32_16x16x32_bf16 v[100:103], v[146:149], v[222:225], v[100:103]
	v_mfma_f32_16x16x32_bf16 v[96:99], v[154:157], v[222:225], v[96:99]
	v_mfma_f32_16x16x32_bf16 v[84:87], v[146:149], v[230:233], v[84:87]
	v_mfma_f32_16x16x32_bf16 v[80:83], v[154:157], v[230:233], v[80:83]
	v_mfma_f32_16x16x32_bf16 v[108:111], v[164:167], v[180:183], v[108:111]
	v_mfma_f32_16x16x32_bf16 v[104:107], v[172:175], v[180:183], v[104:107]
	v_mfma_f32_16x16x32_bf16 v[92:95], v[164:167], v[188:191], v[92:95]
	v_mfma_f32_16x16x32_bf16 v[88:91], v[172:175], v[188:191], v[88:91]
	v_mfma_f32_16x16x32_bf16 v[76:79], v[164:167], v[196:199], v[76:79]
	v_mfma_f32_16x16x32_bf16 v[72:75], v[172:175], v[196:199], v[72:75]
	v_mfma_f32_16x16x32_bf16 v[68:71], v[164:167], v[226:229], v[68:71]
	v_mfma_f32_16x16x32_bf16 v[64:67], v[172:175], v[226:229], v[64:67]
	v_mfma_f32_16x16x32_bf16 v[108:111], v[168:171], v[184:187], v[108:111]
	v_mfma_f32_16x16x32_bf16 v[104:107], v[176:179], v[184:187], v[104:107]
	v_mfma_f32_16x16x32_bf16 v[92:95], v[168:171], v[192:195], v[92:95]
	v_mfma_f32_16x16x32_bf16 v[88:91], v[176:179], v[192:195], v[88:91]
	v_mfma_f32_16x16x32_bf16 v[76:79], v[168:171], v[222:225], v[76:79]
	v_mfma_f32_16x16x32_bf16 v[72:75], v[176:179], v[222:225], v[72:75]
	v_mfma_f32_16x16x32_bf16 v[68:71], v[168:171], v[230:233], v[68:71]
	v_mfma_f32_16x16x32_bf16 v[64:67], v[176:179], v[230:233], v[64:67]
	s_setprio 0
	s_barrier
	s_add_i32 s56, s72, s24
	s_mov_b32 m0, s56
	ds_read_b128 v[180:183], v141 offset:49152
	ds_read_b128 v[184:187], v141 offset:50176
	ds_read_b128 v[188:191], v141 offset:51200
	ds_read_b128 v[192:195], v141 offset:52224
	ds_read_b128 v[196:199], v141 offset:53248
	ds_read_b128 v[222:225], v141 offset:54272
	ds_read_b128 v[226:229], v141 offset:55296
	ds_read_b128 v[230:233], v141 offset:56320
	s_add_u32 s52, s52, 0x80
	s_addc_u32 s53, s53, 0
	global_load_lds_dwordx4 v160, s[52:53]
	s_add_i32 m0, s56, 0x2000
	s_add_i32 s56, s73, s24
	global_load_lds_dwordx4 v128, s[52:53]
	s_add_u32 s52, s52, 0x160000
	s_addc_u32 s53, s53, 0
	s_mov_b32 m0, s56
	s_nop 0
	global_load_lds_dwordx4 v160, s[52:53]
	s_add_i32 m0, s56, 0x2000
	s_nop 0
	global_load_lds_dwordx4 v128, s[52:53]
	s_mov_b32 m0, s74
	s_nop 0
	global_load_lds_dwordx4 v132, s[98:99]
	s_mov_b32 m0, s75
	s_nop 0
	global_load_lds_dwordx4 v130, s[98:99]
	s_waitcnt vmcnt(8)
	s_waitcnt lgkmcnt(0)
	s_barrier
	s_setprio 1
	v_mfma_f32_16x16x32_bf16 v[60:63], v[142:145], v[180:183], v[60:63]
	v_mfma_f32_16x16x32_bf16 v[56:59], v[150:153], v[180:183], v[56:59]
	v_mfma_f32_16x16x32_bf16 v[52:55], v[142:145], v[188:191], v[52:55]
	v_mfma_f32_16x16x32_bf16 v[48:51], v[150:153], v[188:191], v[48:51]
	v_mfma_f32_16x16x32_bf16 v[36:39], v[142:145], v[196:199], v[36:39]
	v_mfma_f32_16x16x32_bf16 v[32:35], v[150:153], v[196:199], v[32:35]
	v_mfma_f32_16x16x32_bf16 v[20:23], v[142:145], v[226:229], v[20:23]
	v_mfma_f32_16x16x32_bf16 v[16:19], v[150:153], v[226:229], v[16:19]
	v_mfma_f32_16x16x32_bf16 v[60:63], v[146:149], v[184:187], v[60:63]
	v_mfma_f32_16x16x32_bf16 v[56:59], v[154:157], v[184:187], v[56:59]
	v_mfma_f32_16x16x32_bf16 v[52:55], v[146:149], v[192:195], v[52:55]
	v_mfma_f32_16x16x32_bf16 v[48:51], v[154:157], v[192:195], v[48:51]
	v_mfma_f32_16x16x32_bf16 v[36:39], v[146:149], v[222:225], v[36:39]
	v_mfma_f32_16x16x32_bf16 v[32:35], v[154:157], v[222:225], v[32:35]
	v_mfma_f32_16x16x32_bf16 v[20:23], v[146:149], v[230:233], v[20:23]
	v_mfma_f32_16x16x32_bf16 v[16:19], v[154:157], v[230:233], v[16:19]
	v_mfma_f32_16x16x32_bf16 v[44:47], v[164:167], v[180:183], v[44:47]
	v_mfma_f32_16x16x32_bf16 v[40:43], v[172:175], v[180:183], v[40:43]
	v_mfma_f32_16x16x32_bf16 v[28:31], v[164:167], v[188:191], v[28:31]
	v_mfma_f32_16x16x32_bf16 v[24:27], v[172:175], v[188:191], v[24:27]
	v_mfma_f32_16x16x32_bf16 v[12:15], v[164:167], v[196:199], v[12:15]
	v_mfma_f32_16x16x32_bf16 v[8:11], v[172:175], v[196:199], v[8:11]
	v_mfma_f32_16x16x32_bf16 v[4:7], v[164:167], v[226:229], v[4:7]
	v_mfma_f32_16x16x32_bf16 v[0:3], v[172:175], v[226:229], v[0:3]
	v_mfma_f32_16x16x32_bf16 v[44:47], v[168:171], v[184:187], v[44:47]
	v_mfma_f32_16x16x32_bf16 v[40:43], v[176:179], v[184:187], v[40:43]
	v_mfma_f32_16x16x32_bf16 v[28:31], v[168:171], v[192:195], v[28:31]
	v_mfma_f32_16x16x32_bf16 v[24:27], v[176:179], v[192:195], v[24:27]
	v_mfma_f32_16x16x32_bf16 v[12:15], v[168:171], v[222:225], v[12:15]
	v_mfma_f32_16x16x32_bf16 v[8:11], v[176:179], v[222:225], v[8:11]
	v_mfma_f32_16x16x32_bf16 v[4:7], v[168:171], v[230:233], v[4:7]
	v_mfma_f32_16x16x32_bf16 v[0:3], v[176:179], v[230:233], v[0:3]
	s_setprio 0
	s_barrier
	s_add_i32 s83, s83, 2
	s_add_u32 s81, s81, 0x100
	s_addc_u32 s82, s82, 0
	s_cmpk_gt_u32 s83, 0x55
	s_mov_b64 s[72:73], s[4:5]
	s_cbranch_scc0 .LBB0_52
	s_and_b64 vcc, exec, s[42:43]
	s_cbranch_vccz .LBB0_55
	s_barrier

; #define PG8_STAGE(bufoff, gbase, voff) do { _Pragma("unroll") for (int _i = 0; _i < 2; ++_i) \
;         __builtin_amdgcn_global_load_lds((const unsigned*)((const char*)(gbase) + (voff)[_i]), (PG8_LAS unsigned*)(lds + (bufoff) + ldsw + _i * 8192), 16, 0, 0); } while (0)
; #define PG8_LDA(dst, b, h) do { _Pragma("unroll") for (int m = 0; m < 4; ++m) _Pragma("unroll") for (int k = 0; k < 2; ++k) dst[m][k] = *(const PG8_LAS bf16x8*)(lds + PG8_SA(b, h) + aoff + m * 2048 + k * 1024); } while (0)
; #define PG8_LDB(dst, b, h) do { _Pragma("unroll") for (int n = 0; n < 2; ++n) _Pragma("unroll") for (int k = 0; k < 2; ++k) dst[n][k] = *(const PG8_LAS bf16x8*)(lds + PG8_SB(b, h) + boff + n * 2048 + k * 1024); } while (0)
; #define PG8_MMA(ai, bj, At, Bt) do { __builtin_amdgcn_s_setprio(1); _Pragma("unroll") for (int m = 0; m < 4; ++m) _Pragma("unroll") for (int n = 0; n < 2; ++n) _Pragma("unroll") for (int k = 0; k < 2; ++k) \
;         acc[ai][bj][m][n] = __builtin_amdgcn_mfma_f32_16x16x32_bf16(Bt[n][k], At[m][k], acc[ai][bj][m][n], 0, 0, 0); __builtin_amdgcn_s_setprio(0); } while (0)
; #define PG8_WAIT_V(n) asm volatile("s_waitcnt vmcnt(" #n ")" ::: "memory")
; #define PG8_WAIT_L(n) asm volatile("s_waitcnt lgkmcnt(" #n ")" ::: "memory")
; template <class Epi, class Sched, bool ALIGN_EPI = false, bool SP2 = false>
; __device__ __forceinline__ void gemm_phase(PG8_LAS unsigned char* lds, const Gemm g, const Sched& S, const Epi& E) {
;     ...
;             const bool last = (t == nt - 2);
;             const char* a1 = cA + (size_t)(t + 1) * kstep;
;             const char* a2 = last ? nA : cA + (size_t)(t + 2) * kstep; const char* b2 = last ? nB : cB + (size_t)(t + 2) * kstep;
;             const char* a3 = a2 + kstep; const char* b3 = b2 + kstep;
;             if (last && has_next) S.a_ready(nxt);
;             if constexpr (SP2) {
;             PG8_LDB(B0, 0, 0); PG8_LDB(B1, 0, 1); PG8_SCHED; PG8_LDA(At, 0, 0); PG8_STAGE(PG8_SA(1, 1), a1 + hstep, voffA);
;             PG8_WAIT_V(8); PG8_WAIT_L(0); PG8_BAR; PG8_MMA(0, 0, At, B0); PG8_MMA(0, 1, At, B1); PG8_BAR; PG8_SCHED;
;             PG8_LDA(At, 0, 1); PG8_STAGE(PG8_SB(0, 0), b2, voffB); PG8_STAGE(PG8_SB(0, 1), b2 + hstep, voffB); PG8_STAGE(PG8_SA(0, 0), a2, voffA);
;             PG8_WAIT_V(8); PG8_WAIT_L(0); PG8_BAR; PG8_MMA(1, 0, At, B0); PG8_MMA(1, 1, At, B1); PG8_BAR; PG8_SCHED;
.LBB0_86:
	s_add_i32 s88, 0, 0x10000
	s_add_i32 s90, 0, 0x14000
	ds_read_b128 v[140:143], v200
	ds_read_b128 v[150:153], v200 offset:1024
	ds_read_b128 v[154:157], v200 offset:2048
	ds_read_b128 v[164:167], v200 offset:3072
	ds_read_b128 v[168:171], v200 offset:16384
	ds_read_b128 v[172:175], v200 offset:17408
	ds_read_b128 v[176:179], v200 offset:18432
	ds_read_b128 v[180:183], v200 offset:19456
	s_add_i32 m0, s63, 0xc000
	ds_read_b128 v[184:187], v149
	ds_read_b128 v[188:191], v149 offset:1024
	ds_read_b128 v[192:195], v149 offset:2048
	ds_read_b128 v[196:199], v149 offset:3072
	ds_read_b128 v[222:225], v149 offset:4096
	ds_read_b128 v[226:229], v149 offset:5120
	ds_read_b128 v[230:233], v149 offset:6144
	ds_read_b128 v[234:237], v149 offset:7168
	global_load_lds_dwordx4 v136, s[82:83]
	s_add_i32 m0, s63, 0xe000
	s_nop 0
	global_load_lds_dwordx4 v138, s[82:83]
	s_add_u32 s4, s82, 0xfffc0080
	s_addc_u32 s5, s83, -1
	s_cmp_eq_u32 s87, 12
	s_cselect_b32 s53, s7, s5
	s_cselect_b32 s52, s15, s4
	s_cselect_b32 s5, s24, s43
	s_cselect_b32 s4, s28, s29
	s_waitcnt vmcnt(8)
	s_waitcnt lgkmcnt(0)
	s_barrier
	s_setprio 1
	v_mfma_f32_16x16x32_bf16 v[124:127], v[140:143], v[184:187], v[124:127]
	v_mfma_f32_16x16x32_bf16 v[120:123], v[154:157], v[184:187], v[120:123]
	v_mfma_f32_16x16x32_bf16 v[108:111], v[140:143], v[192:195], v[108:111]
	v_mfma_f32_16x16x32_bf16 v[104:107], v[154:157], v[192:195], v[104:107]
	v_mfma_f32_16x16x32_bf16 v[92:95], v[140:143], v[222:225], v[92:95]
	v_mfma_f32_16x16x32_bf16 v[88:91], v[154:157], v[222:225], v[88:91]
	v_mfma_f32_16x16x32_bf16 v[76:79], v[140:143], v[230:233], v[76:79]
	v_mfma_f32_16x16x32_bf16 v[72:75], v[154:157], v[230:233], v[72:75]
	v_mfma_f32_16x16x32_bf16 v[124:127], v[150:153], v[188:191], v[124:127]
	v_mfma_f32_16x16x32_bf16 v[120:123], v[164:167], v[188:191], v[120:123]
	v_mfma_f32_16x16x32_bf16 v[108:111], v[150:153], v[196:199], v[108:111]
	v_mfma_f32_16x16x32_bf16 v[104:107], v[164:167], v[196:199], v[104:107]
	v_mfma_f32_16x16x32_bf16 v[92:95], v[150:153], v[226:229], v[92:95]
	v_mfma_f32_16x16x32_bf16 v[88:91], v[164:167], v[226:229], v[88:91]
	v_mfma_f32_16x16x32_bf16 v[76:79], v[150:153], v[234:237], v[76:79]
	v_mfma_f32_16x16x32_bf16 v[72:75], v[164:167], v[234:237], v[72:75]
	v_mfma_f32_16x16x32_bf16 v[116:119], v[168:171], v[184:187], v[116:119]
	v_mfma_f32_16x16x32_bf16 v[112:115], v[176:179], v[184:187], v[112:115]
	v_mfma_f32_16x16x32_bf16 v[100:103], v[168:171], v[192:195], v[100:103]
	v_mfma_f32_16x16x32_bf16 v[96:99], v[176:179], v[192:195], v[96:99]
	v_mfma_f32_16x16x32_bf16 v[84:87], v[168:171], v[222:225], v[84:87]
	v_mfma_f32_16x16x32_bf16 v[80:83], v[176:179], v[222:225], v[80:83]
	v_mfma_f32_16x16x32_bf16 v[68:71], v[168:171], v[230:233], v[68:71]
	v_mfma_f32_16x16x32_bf16 v[64:67], v[176:179], v[230:233], v[64:67]
	v_mfma_f32_16x16x32_bf16 v[116:119], v[172:175], v[188:191], v[116:119]
	v_mfma_f32_16x16x32_bf16 v[112:115], v[180:183], v[188:191], v[112:115]
	v_mfma_f32_16x16x32_bf16 v[100:103], v[172:175], v[196:199], v[100:103]
	v_mfma_f32_16x16x32_bf16 v[96:99], v[180:183], v[196:199], v[96:99]
	v_mfma_f32_16x16x32_bf16 v[84:87], v[172:175], v[226:229], v[84:87]
	v_mfma_f32_16x16x32_bf16 v[80:83], v[180:183], v[226:229], v[80:83]
	v_mfma_f32_16x16x32_bf16 v[68:71], v[172:175], v[234:237], v[68:71]
	v_mfma_f32_16x16x32_bf16 v[64:67], v[180:183], v[234:237], v[64:67]
	s_setprio 0
	s_barrier
	s_add_i32 s88, s88, s59
	s_mov_b32 m0, s88
	ds_read_b128 v[184:187], v149 offset:16384
	ds_read_b128 v[188:191], v149 offset:17408
	ds_read_b128 v[192:195], v149 offset:18432
	ds_read_b128 v[196:199], v149 offset:19456
	ds_read_b128 v[222:225], v149 offset:20480
	ds_read_b128 v[226:229], v149 offset:21504
	ds_read_b128 v[230:233], v149 offset:22528
	ds_read_b128 v[234:237], v149 offset:23552
	global_load_lds_dwordx4 v130, s[4:5]
	s_add_i32 m0, s88, 0x2000
	s_add_u32 s88, s4, 0x40000
	s_addc_u32 s89, s5, 0
	s_add_i32 s90, s90, s59
	global_load_lds_dwordx4 v134, s[4:5]
	s_mov_b32 m0, s90
	s_nop 0
	global_load_lds_dwordx4 v130, s[88:89]
	s_add_i32 m0, s90, 0x2000
	s_nop 0
	global_load_lds_dwordx4 v134, s[88:89]
	s_mov_b32 m0, s63
	s_nop 0
	global_load_lds_dwordx4 v128, s[52:53]
	s_mov_b32 m0, s74
	s_nop 0
	global_load_lds_dwordx4 v132, s[52:53]
	s_add_u32 s98, s52, 0x80
	s_addc_u32 s99, s53, 0
	s_waitcnt vmcnt(8)
	s_waitcnt lgkmcnt(0)
	s_barrier
	s_setprio 1
	v_mfma_f32_16x16x32_bf16 v[60:63], v[140:143], v[184:187], v[60:63]
	v_mfma_f32_16x16x32_bf16 v[56:59], v[154:157], v[184:187], v[56:59]
	v_mfma_f32_16x16x32_bf16 v[44:47], v[140:143], v[192:195], v[44:47]
	v_mfma_f32_16x16x32_bf16 v[40:43], v[154:157], v[192:195], v[40:43]
	v_mfma_f32_16x16x32_bf16 v[28:31], v[140:143], v[222:225], v[28:31]
	v_mfma_f32_16x16x32_bf16 v[24:27], v[154:157], v[222:225], v[24:27]
	v_mfma_f32_16x16x32_bf16 v[12:15], v[140:143], v[230:233], v[12:15]
	v_mfma_f32_16x16x32_bf16 v[8:11], v[154:157], v[230:233], v[8:11]
	v_mfma_f32_16x16x32_bf16 v[60:63], v[150:153], v[188:191], v[60:63]
	v_mfma_f32_16x16x32_bf16 v[56:59], v[164:167], v[188:191], v[56:59]
	v_mfma_f32_16x16x32_bf16 v[44:47], v[150:153], v[196:199], v[44:47]
	v_mfma_f32_16x16x32_bf16 v[40:43], v[164:167], v[196:199], v[40:43]
	v_mfma_f32_16x16x32_bf16 v[28:31], v[150:153], v[226:229], v[28:31]
	v_mfma_f32_16x16x32_bf16 v[24:27], v[164:167], v[226:229], v[24:27]
	v_mfma_f32_16x16x32_bf16 v[12:15], v[150:153], v[234:237], v[12:15]
	v_mfma_f32_16x16x32_bf16 v[8:11], v[164:167], v[234:237], v[8:11]
	v_mfma_f32_16x16x32_bf16 v[52:55], v[168:171], v[184:187], v[52:55]
	v_mfma_f32_16x16x32_bf16 v[48:51], v[176:179], v[184:187], v[48:51]
	v_mfma_f32_16x16x32_bf16 v[36:39], v[168:171], v[192:195], v[36:39]
	v_mfma_f32_16x16x32_bf16 v[32:35], v[176:179], v[192:195], v[32:35]
	v_mfma_f32_16x16x32_bf16 v[20:23], v[168:171], v[222:225], v[20:23]
	v_mfma_f32_16x16x32_bf16 v[16:19], v[176:179], v[222:225], v[16:19]
	v_mfma_f32_16x16x32_bf16 v[4:7], v[168:171], v[230:233], v[4:7]
	v_mfma_f32_16x16x32_bf16 v[0:3], v[176:179], v[230:233], v[0:3]
	v_mfma_f32_16x16x32_bf16 v[52:55], v[172:175], v[188:191], v[52:55]
	v_mfma_f32_16x16x32_bf16 v[48:51], v[180:183], v[188:191], v[48:51]
	v_mfma_f32_16x16x32_bf16 v[36:39], v[172:175], v[196:199], v[36:39]
	v_mfma_f32_16x16x32_bf16 v[32:35], v[180:183], v[196:199], v[32:35]
	v_mfma_f32_16x16x32_bf16 v[20:23], v[172:175], v[226:229], v[20:23]
	v_mfma_f32_16x16x32_bf16 v[16:19], v[180:183], v[226:229], v[16:19]
	v_mfma_f32_16x16x32_bf16 v[4:7], v[172:175], v[234:237], v[4:7]
	v_mfma_f32_16x16x32_bf16 v[0:3], v[180:183], v[234:237], v[0:3]
	s_setprio 0
	s_barrier
; #define PG8_STAGE(bufoff, gbase, voff) do { _Pragma("unroll") for (int _i = 0; _i < 2; ++_i) \
;         __builtin_amdgcn_global_load_lds((const unsigned*)((const char*)(gbase) + (voff)[_i]), (PG8_LAS unsigned*)(lds + (bufoff) + ldsw + _i * 8192), 16, 0, 0); } while (0)
; #define PG8_LDA(dst, b, h) do { _Pragma("unroll") for (int m = 0; m < 4; ++m) _Pragma("unroll") for (int k = 0; k < 2; ++k) dst[m][k] = *(const PG8_LAS bf16x8*)(lds + PG8_SA(b, h) + aoff + m * 2048 + k * 1024); } while (0)
; #define PG8_LDB(dst, b, h) do { _Pragma("unroll") for (int n = 0; n < 2; ++n) _Pragma("unroll") for (int k = 0; k < 2; ++k) dst[n][k] = *(const PG8_LAS bf16x8*)(lds + PG8_SB(b, h) + boff + n * 2048 + k * 1024); } while (0)
; #define PG8_MMA(ai, bj, At, Bt) do { __builtin_amdgcn_s_setprio(1); _Pragma("unroll") for (int m = 0; m < 4; ++m) _Pragma("unroll") for (int n = 0; n < 2; ++n) _Pragma("unroll") for (int k = 0; k < 2; ++k) \
;         acc[ai][bj][m][n] = __builtin_amdgcn_mfma_f32_16x16x32_bf16(Bt[n][k], At[m][k], acc[ai][bj][m][n], 0, 0, 0); __builtin_amdgcn_s_setprio(0); } while (0)
; #define PG8_WAIT_V(n) asm volatile("s_waitcnt vmcnt(" #n ")" ::: "memory")
; #define PG8_WAIT_L(n) asm volatile("s_waitcnt lgkmcnt(" #n ")" ::: "memory")
; #define PG8_BAR __builtin_amdgcn_s_barrier()
; #define PG8_SCHED __builtin_amdgcn_sched_barrier(0)
; template <class Epi, class Sched, bool ALIGN_EPI = false, bool SP2 = false>
; __device__ __forceinline__ void gemm_phase(PG8_LAS unsigned char* lds, const Gemm g, const Sched& S, const Epi& E) {
;     ...
;             PG8_LDB(B0, 1, 0); PG8_LDB(B1, 1, 1); PG8_SCHED; PG8_LDA(At, 1, 0); PG8_STAGE(PG8_SA(0, 1), a2 + hstep, voffA);
;             PG8_WAIT_V(8); PG8_WAIT_L(0); PG8_BAR; PG8_MMA(0, 0, At, B0); PG8_MMA(0, 1, At, B1); PG8_BAR; PG8_SCHED;
;             PG8_LDA(At, 1, 1); PG8_STAGE(PG8_SB(1, 0), b3, voffB); PG8_STAGE(PG8_SB(1, 1), b3 + hstep, voffB); PG8_STAGE(PG8_SA(1, 0), a3, voffA);
;             PG8_WAIT_V(8); PG8_WAIT_L(0); PG8_BAR; PG8_MMA(1, 0, At, B0); PG8_MMA(1, 1, At, B1); PG8_BAR; PG8_SCHED;
;     ...
;         if constexpr (ALIGN_EPI) { if (wr == 0) PG8_BAR; }
	s_add_i32 s88, 0, 0x18000
	s_add_i32 s89, 0, 0x1c000
	ds_read_b128 v[140:143], v200 offset:32768
	ds_read_b128 v[150:153], v200 offset:33792
	ds_read_b128 v[154:157], v200 offset:34816
	ds_read_b128 v[164:167], v200 offset:35840
	ds_read_b128 v[168:171], v200 offset:49152
	ds_read_b128 v[172:175], v200 offset:50176
	ds_read_b128 v[176:179], v200 offset:51200
	ds_read_b128 v[180:183], v200 offset:52224
	s_add_u32 s52, s52, 0x40000
	s_addc_u32 s53, s53, 0
	s_mov_b32 m0, s75
	ds_read_b128 v[184:187], v149 offset:32768
	ds_read_b128 v[188:191], v149 offset:33792
	ds_read_b128 v[192:195], v149 offset:34816
	ds_read_b128 v[196:199], v149 offset:35840
	ds_read_b128 v[222:225], v149 offset:36864
	ds_read_b128 v[226:229], v149 offset:37888
	ds_read_b128 v[230:233], v149 offset:38912
	ds_read_b128 v[234:237], v149 offset:39936
	global_load_lds_dwordx4 v128, s[52:53]
	s_mov_b32 m0, s81
	s_nop 0
	global_load_lds_dwordx4 v132, s[52:53]
	s_waitcnt vmcnt(8)
	s_waitcnt lgkmcnt(0)
	s_barrier
	s_setprio 1
	v_mfma_f32_16x16x32_bf16 v[124:127], v[140:143], v[184:187], v[124:127]
	v_mfma_f32_16x16x32_bf16 v[120:123], v[154:157], v[184:187], v[120:123]
	v_mfma_f32_16x16x32_bf16 v[108:111], v[140:143], v[192:195], v[108:111]
	v_mfma_f32_16x16x32_bf16 v[104:107], v[154:157], v[192:195], v[104:107]
	v_mfma_f32_16x16x32_bf16 v[92:95], v[140:143], v[222:225], v[92:95]
	v_mfma_f32_16x16x32_bf16 v[88:91], v[154:157], v[222:225], v[88:91]
	v_mfma_f32_16x16x32_bf16 v[76:79], v[140:143], v[230:233], v[76:79]
	v_mfma_f32_16x16x32_bf16 v[72:75], v[154:157], v[230:233], v[72:75]
	v_mfma_f32_16x16x32_bf16 v[124:127], v[150:153], v[188:191], v[124:127]
	v_mfma_f32_16x16x32_bf16 v[120:123], v[164:167], v[188:191], v[120:123]
	v_mfma_f32_16x16x32_bf16 v[108:111], v[150:153], v[196:199], v[108:111]
	v_mfma_f32_16x16x32_bf16 v[104:107], v[164:167], v[196:199], v[104:107]
	v_mfma_f32_16x16x32_bf16 v[92:95], v[150:153], v[226:229], v[92:95]
	v_mfma_f32_16x16x32_bf16 v[88:91], v[164:167], v[226:229], v[88:91]
	v_mfma_f32_16x16x32_bf16 v[76:79], v[150:153], v[234:237], v[76:79]
	v_mfma_f32_16x16x32_bf16 v[72:75], v[164:167], v[234:237], v[72:75]
	v_mfma_f32_16x16x32_bf16 v[116:119], v[168:171], v[184:187], v[116:119]
	v_mfma_f32_16x16x32_bf16 v[112:115], v[176:179], v[184:187], v[112:115]
	v_mfma_f32_16x16x32_bf16 v[100:103], v[168:171], v[192:195], v[100:103]
	v_mfma_f32_16x16x32_bf16 v[96:99], v[176:179], v[192:195], v[96:99]
	v_mfma_f32_16x16x32_bf16 v[84:87], v[168:171], v[222:225], v[84:87]
	v_mfma_f32_16x16x32_bf16 v[80:83], v[176:179], v[222:225], v[80:83]
	v_mfma_f32_16x16x32_bf16 v[68:71], v[168:171], v[230:233], v[68:71]
	v_mfma_f32_16x16x32_bf16 v[64:67], v[176:179], v[230:233], v[64:67]
	v_mfma_f32_16x16x32_bf16 v[116:119], v[172:175], v[188:191], v[116:119]
	v_mfma_f32_16x16x32_bf16 v[112:115], v[180:183], v[188:191], v[112:115]
	v_mfma_f32_16x16x32_bf16 v[100:103], v[172:175], v[196:199], v[100:103]
	v_mfma_f32_16x16x32_bf16 v[96:99], v[180:183], v[196:199], v[96:99]
	v_mfma_f32_16x16x32_bf16 v[84:87], v[172:175], v[226:229], v[84:87]
	v_mfma_f32_16x16x32_bf16 v[80:83], v[180:183], v[226:229], v[80:83]
	v_mfma_f32_16x16x32_bf16 v[68:71], v[172:175], v[234:237], v[68:71]
	v_mfma_f32_16x16x32_bf16 v[64:67], v[180:183], v[234:237], v[64:67]
	s_setprio 0
	s_barrier
	s_add_i32 s52, s88, s59
	s_mov_b32 m0, s52
	ds_read_b128 v[184:187], v149 offset:49152
	ds_read_b128 v[188:191], v149 offset:50176
	ds_read_b128 v[192:195], v149 offset:51200
	ds_read_b128 v[196:199], v149 offset:52224
	ds_read_b128 v[222:225], v149 offset:53248
	ds_read_b128 v[226:229], v149 offset:54272
	ds_read_b128 v[230:233], v149 offset:55296
	ds_read_b128 v[234:237], v149 offset:56320
	s_add_u32 s4, s4, 0x80
	s_addc_u32 s5, s5, 0
	global_load_lds_dwordx4 v130, s[4:5]
	s_add_i32 m0, s52, 0x2000
	s_add_i32 s52, s89, s59
	global_load_lds_dwordx4 v134, s[4:5]
	s_add_u32 s4, s4, 0x40000
	s_addc_u32 s5, s5, 0
	s_mov_b32 m0, s52
	s_nop 0
	global_load_lds_dwordx4 v130, s[4:5]
	s_add_i32 m0, s52, 0x2000
	s_nop 0
	global_load_lds_dwordx4 v134, s[4:5]
	s_mov_b32 m0, s84
	s_nop 0
	global_load_lds_dwordx4 v128, s[98:99]
	s_mov_b32 m0, s85
	s_nop 0
	global_load_lds_dwordx4 v132, s[98:99]
	s_waitcnt vmcnt(8)
	s_waitcnt lgkmcnt(0)
	s_barrier
	s_setprio 1
	v_mfma_f32_16x16x32_bf16 v[60:63], v[140:143], v[184:187], v[60:63]
	v_mfma_f32_16x16x32_bf16 v[56:59], v[154:157], v[184:187], v[56:59]
	v_mfma_f32_16x16x32_bf16 v[44:47], v[140:143], v[192:195], v[44:47]
	v_mfma_f32_16x16x32_bf16 v[40:43], v[154:157], v[192:195], v[40:43]
	v_mfma_f32_16x16x32_bf16 v[28:31], v[140:143], v[222:225], v[28:31]
	v_mfma_f32_16x16x32_bf16 v[24:27], v[154:157], v[222:225], v[24:27]
	v_mfma_f32_16x16x32_bf16 v[12:15], v[140:143], v[230:233], v[12:15]
	v_mfma_f32_16x16x32_bf16 v[8:11], v[154:157], v[230:233], v[8:11]
	v_mfma_f32_16x16x32_bf16 v[60:63], v[150:153], v[188:191], v[60:63]
	v_mfma_f32_16x16x32_bf16 v[56:59], v[164:167], v[188:191], v[56:59]
	v_mfma_f32_16x16x32_bf16 v[44:47], v[150:153], v[196:199], v[44:47]
	v_mfma_f32_16x16x32_bf16 v[40:43], v[164:167], v[196:199], v[40:43]
	v_mfma_f32_16x16x32_bf16 v[28:31], v[150:153], v[226:229], v[28:31]
	v_mfma_f32_16x16x32_bf16 v[24:27], v[164:167], v[226:229], v[24:27]
	v_mfma_f32_16x16x32_bf16 v[12:15], v[150:153], v[234:237], v[12:15]
	v_mfma_f32_16x16x32_bf16 v[8:11], v[164:167], v[234:237], v[8:11]
	v_mfma_f32_16x16x32_bf16 v[52:55], v[168:171], v[184:187], v[52:55]
	v_mfma_f32_16x16x32_bf16 v[48:51], v[176:179], v[184:187], v[48:51]
	v_mfma_f32_16x16x32_bf16 v[36:39], v[168:171], v[192:195], v[36:39]
	v_mfma_f32_16x16x32_bf16 v[32:35], v[176:179], v[192:195], v[32:35]
	v_mfma_f32_16x16x32_bf16 v[20:23], v[168:171], v[222:225], v[20:23]
	v_mfma_f32_16x16x32_bf16 v[16:19], v[176:179], v[222:225], v[16:19]
	v_mfma_f32_16x16x32_bf16 v[4:7], v[168:171], v[230:233], v[4:7]
	v_mfma_f32_16x16x32_bf16 v[0:3], v[176:179], v[230:233], v[0:3]
	v_mfma_f32_16x16x32_bf16 v[52:55], v[172:175], v[188:191], v[52:55]
	v_mfma_f32_16x16x32_bf16 v[48:51], v[180:183], v[188:191], v[48:51]
	v_mfma_f32_16x16x32_bf16 v[36:39], v[172:175], v[196:199], v[36:39]
	v_mfma_f32_16x16x32_bf16 v[32:35], v[180:183], v[196:199], v[32:35]
	v_mfma_f32_16x16x32_bf16 v[20:23], v[172:175], v[226:229], v[20:23]
	v_mfma_f32_16x16x32_bf16 v[16:19], v[180:183], v[226:229], v[16:19]
	v_mfma_f32_16x16x32_bf16 v[4:7], v[172:175], v[234:237], v[4:7]
	v_mfma_f32_16x16x32_bf16 v[0:3], v[180:183], v[234:237], v[0:3]
	s_setprio 0
	s_barrier
	s_add_i32 s87, s87, 2
	s_add_u32 s82, s82, 0x100
	s_addc_u32 s83, s83, 0
	s_add_u32 s29, s29, 0x100
	s_addc_u32 s43, s43, 0
	s_cmp_gt_u32 s87, 13
	s_cbranch_scc0 .LBB0_86
	s_and_b64 vcc, exec, s[12:13]
	s_cbranch_vccz .LBB0_89
	s_barrier

; #define PG8_STAGE(bufoff, gbase, voff) do { _Pragma("unroll") for (int _i = 0; _i < 2; ++_i) \
;         __builtin_amdgcn_global_load_lds((const unsigned*)((const char*)(gbase) + (voff)[_i]), (PG8_LAS unsigned*)(lds + (bufoff) + ldsw + _i * 8192), 16, 0, 0); } while (0)
; #define PG8_LDA(dst, b, h) do { _Pragma("unroll") for (int m = 0; m < 4; ++m) _Pragma("unroll") for (int k = 0; k < 2; ++k) dst[m][k] = *(const PG8_LAS bf16x8*)(lds + PG8_SA(b, h) + aoff + m * 2048 + k * 1024); } while (0)
; #define PG8_LDB(dst, b, h) do { _Pragma("unroll") for (int n = 0; n < 2; ++n) _Pragma("unroll") for (int k = 0; k < 2; ++k) dst[n][k] = *(const PG8_LAS bf16x8*)(lds + PG8_SB(b, h) + boff + n * 2048 + k * 1024); } while (0)
; #define PG8_MMA(ai, bj, At, Bt) do { __builtin_amdgcn_s_setprio(1); _Pragma("unroll") for (int m = 0; m < 4; ++m) _Pragma("unroll") for (int n = 0; n < 2; ++n) _Pragma("unroll") for (int k = 0; k < 2; ++k) \
;         acc[ai][bj][m][n] = __builtin_amdgcn_mfma_f32_16x16x32_bf16(Bt[n][k], At[m][k], acc[ai][bj][m][n], 0, 0, 0); __builtin_amdgcn_s_setprio(0); } while (0)
; #define PG8_WAIT_V(n) asm volatile("s_waitcnt vmcnt(" #n ")" ::: "memory")
; #define PG8_WAIT_L(n) asm volatile("s_waitcnt lgkmcnt(" #n ")" ::: "memory")
; template <class Epi, class Sched, bool ALIGN_EPI = false, bool SP2 = false>
; __device__ __forceinline__ void gemm_phase(PG8_LAS unsigned char* lds, const Gemm g, const Sched& S, const Epi& E) {
;     ...
;             const bool last = (t == nt - 2);
;             const char* a1 = cA + (size_t)(t + 1) * kstep;
;             const char* a2 = last ? nA : cA + (size_t)(t + 2) * kstep; const char* b2 = last ? nB : cB + (size_t)(t + 2) * kstep;
;             const char* a3 = a2 + kstep; const char* b3 = b2 + kstep;
;             if (last && has_next) S.a_ready(nxt);
;             if constexpr (SP2) {
;             PG8_LDB(B0, 0, 0); PG8_LDB(B1, 0, 1); PG8_SCHED; PG8_LDA(At, 0, 0); PG8_STAGE(PG8_SA(1, 1), a1 + hstep, voffA);
;             PG8_WAIT_V(8); PG8_WAIT_L(0); PG8_BAR; PG8_MMA(0, 0, At, B0); PG8_MMA(0, 1, At, B1); PG8_BAR; PG8_SCHED;
;             PG8_LDA(At, 0, 1); PG8_STAGE(PG8_SB(0, 0), b2, voffB); PG8_STAGE(PG8_SB(0, 1), b2 + hstep, voffB); PG8_STAGE(PG8_SA(0, 0), a2, voffA);
;             PG8_WAIT_V(8); PG8_WAIT_L(0); PG8_BAR; PG8_MMA(1, 0, At, B0); PG8_MMA(1, 1, At, B1); PG8_BAR; PG8_SCHED;
.LBB0_322:
	s_add_i32 s56, 0, 0x10000
	s_add_i32 vcc_lo, 0, 0x14000
	s_waitcnt lgkmcnt(0)
	ds_read_b128 v[154:157], v246
	ds_read_b128 v[164:167], v246 offset:1024
	ds_read_b128 v[168:171], v246 offset:2048
	ds_read_b128 v[172:175], v246 offset:3072
	ds_read_b128 v[176:179], v246 offset:16384
	ds_read_b128 v[180:183], v246 offset:17408
	ds_read_b128 v[184:187], v246 offset:18432
	ds_read_b128 v[188:191], v246 offset:19456
	s_add_i32 m0, s89, 0xc000
	ds_read_b128 v[192:195], v145
	ds_read_b128 v[196:199], v145 offset:1024
	ds_read_b128 v[222:225], v145 offset:2048
	ds_read_b128 v[226:229], v145 offset:3072
	ds_read_b128 v[230:233], v145 offset:4096
	ds_read_b128 v[234:237], v145 offset:5120
	ds_read_b128 v[238:241], v145 offset:6144
	ds_read_b128 v[242:245], v145 offset:7168
	global_load_lds_dwordx4 v150, s[14:15]
	s_add_i32 m0, s89, 0xe000
	s_nop 0
	global_load_lds_dwordx4 v152, s[14:15]
	s_add_u32 s4, s14, 0xfff80080
	s_addc_u32 s5, s15, -1
	s_cmp_eq_u32 s55, 28
	s_cselect_b32 s53, s1, s5
	s_cselect_b32 s52, s28, s4
	s_cselect_b32 s5, s29, s54
	s_cselect_b32 s4, s43, s45
	s_waitcnt vmcnt(8)
	s_waitcnt lgkmcnt(0)
	s_barrier
	s_setprio 1
	v_mfma_f32_16x16x32_bf16 v[124:127], v[154:157], v[192:195], v[124:127]
	v_mfma_f32_16x16x32_bf16 v[120:123], v[168:171], v[192:195], v[120:123]
	v_mfma_f32_16x16x32_bf16 v[116:119], v[154:157], v[222:225], v[116:119]
	v_mfma_f32_16x16x32_bf16 v[112:115], v[168:171], v[222:225], v[112:115]
	v_mfma_f32_16x16x32_bf16 v[108:111], v[154:157], v[230:233], v[108:111]
	v_mfma_f32_16x16x32_bf16 v[104:107], v[168:171], v[230:233], v[104:107]
	v_mfma_f32_16x16x32_bf16 v[100:103], v[154:157], v[238:241], v[100:103]
	v_mfma_f32_16x16x32_bf16 v[96:99], v[168:171], v[238:241], v[96:99]
	v_mfma_f32_16x16x32_bf16 v[124:127], v[164:167], v[196:199], v[124:127]
	v_mfma_f32_16x16x32_bf16 v[120:123], v[172:175], v[196:199], v[120:123]
	v_mfma_f32_16x16x32_bf16 v[116:119], v[164:167], v[226:229], v[116:119]
	v_mfma_f32_16x16x32_bf16 v[112:115], v[172:175], v[226:229], v[112:115]
	v_mfma_f32_16x16x32_bf16 v[108:111], v[164:167], v[234:237], v[108:111]
	v_mfma_f32_16x16x32_bf16 v[104:107], v[172:175], v[234:237], v[104:107]
	v_mfma_f32_16x16x32_bf16 v[100:103], v[164:167], v[242:245], v[100:103]
	v_mfma_f32_16x16x32_bf16 v[96:99], v[172:175], v[242:245], v[96:99]
	v_mfma_f32_16x16x32_bf16 v[92:95], v[176:179], v[192:195], v[92:95]
	v_mfma_f32_16x16x32_bf16 v[88:91], v[184:187], v[192:195], v[88:91]
	v_mfma_f32_16x16x32_bf16 v[84:87], v[176:179], v[222:225], v[84:87]
	v_mfma_f32_16x16x32_bf16 v[80:83], v[184:187], v[222:225], v[80:83]
	v_mfma_f32_16x16x32_bf16 v[76:79], v[176:179], v[230:233], v[76:79]
	v_mfma_f32_16x16x32_bf16 v[72:75], v[184:187], v[230:233], v[72:75]
	v_mfma_f32_16x16x32_bf16 v[68:71], v[176:179], v[238:241], v[68:71]
	v_mfma_f32_16x16x32_bf16 v[64:67], v[184:187], v[238:241], v[64:67]
	v_mfma_f32_16x16x32_bf16 v[92:95], v[180:183], v[196:199], v[92:95]
	v_mfma_f32_16x16x32_bf16 v[88:91], v[188:191], v[196:199], v[88:91]
	v_mfma_f32_16x16x32_bf16 v[84:87], v[180:183], v[226:229], v[84:87]
	v_mfma_f32_16x16x32_bf16 v[80:83], v[188:191], v[226:229], v[80:83]
	v_mfma_f32_16x16x32_bf16 v[76:79], v[180:183], v[234:237], v[76:79]
	v_mfma_f32_16x16x32_bf16 v[72:75], v[188:191], v[234:237], v[72:75]
	v_mfma_f32_16x16x32_bf16 v[68:71], v[180:183], v[242:245], v[68:71]
	v_mfma_f32_16x16x32_bf16 v[64:67], v[188:191], v[242:245], v[64:67]
	s_setprio 0
	s_barrier
	s_add_i32 s56, s56, s63
	s_mov_b32 m0, s56
	ds_read_b128 v[192:195], v145 offset:16384
	ds_read_b128 v[196:199], v145 offset:17408
	ds_read_b128 v[222:225], v145 offset:18432
	ds_read_b128 v[226:229], v145 offset:19456
	ds_read_b128 v[230:233], v145 offset:20480
	ds_read_b128 v[234:237], v145 offset:21504
	ds_read_b128 v[238:241], v145 offset:22528
	ds_read_b128 v[242:245], v145 offset:23552
	global_load_lds_dwordx4 v130, s[4:5]
	s_add_i32 m0, s56, 0x2000
	s_add_u32 s56, s4, 0x80000
	s_addc_u32 s57, s5, 0
	s_add_i32 vcc_lo, vcc_lo, s63
	global_load_lds_dwordx4 v134, s[4:5]
	s_mov_b32 m0, vcc_lo
	s_nop 0
	global_load_lds_dwordx4 v130, s[56:57]
	s_add_i32 m0, vcc_lo, 0x2000
	s_nop 0
	global_load_lds_dwordx4 v134, s[56:57]
	s_mov_b32 m0, s89
	s_nop 0
	global_load_lds_dwordx4 v128, s[52:53]
	s_mov_b32 m0, s91
	s_nop 0
	global_load_lds_dwordx4 v132, s[52:53]
	s_add_u32 s98, s52, 0x80
	s_addc_u32 s99, s53, 0
	s_waitcnt vmcnt(8)
	s_waitcnt lgkmcnt(0)
	s_barrier
	s_setprio 1
	v_mfma_f32_16x16x32_bf16 v[60:63], v[154:157], v[192:195], v[60:63]
	v_mfma_f32_16x16x32_bf16 v[56:59], v[168:171], v[192:195], v[56:59]
	v_mfma_f32_16x16x32_bf16 v[52:55], v[154:157], v[222:225], v[52:55]
	v_mfma_f32_16x16x32_bf16 v[48:51], v[168:171], v[222:225], v[48:51]
	v_mfma_f32_16x16x32_bf16 v[44:47], v[154:157], v[230:233], v[44:47]
	v_mfma_f32_16x16x32_bf16 v[40:43], v[168:171], v[230:233], v[40:43]
	v_mfma_f32_16x16x32_bf16 v[36:39], v[154:157], v[238:241], v[36:39]
	v_mfma_f32_16x16x32_bf16 v[32:35], v[168:171], v[238:241], v[32:35]
	v_mfma_f32_16x16x32_bf16 v[60:63], v[164:167], v[196:199], v[60:63]
	v_mfma_f32_16x16x32_bf16 v[56:59], v[172:175], v[196:199], v[56:59]
	v_mfma_f32_16x16x32_bf16 v[52:55], v[164:167], v[226:229], v[52:55]
	v_mfma_f32_16x16x32_bf16 v[48:51], v[172:175], v[226:229], v[48:51]
	v_mfma_f32_16x16x32_bf16 v[44:47], v[164:167], v[234:237], v[44:47]
	v_mfma_f32_16x16x32_bf16 v[40:43], v[172:175], v[234:237], v[40:43]
	v_mfma_f32_16x16x32_bf16 v[36:39], v[164:167], v[242:245], v[36:39]
	v_mfma_f32_16x16x32_bf16 v[32:35], v[172:175], v[242:245], v[32:35]
	v_mfma_f32_16x16x32_bf16 v[28:31], v[176:179], v[192:195], v[28:31]
	v_mfma_f32_16x16x32_bf16 v[24:27], v[184:187], v[192:195], v[24:27]
	v_mfma_f32_16x16x32_bf16 v[20:23], v[176:179], v[222:225], v[20:23]
	v_mfma_f32_16x16x32_bf16 v[16:19], v[184:187], v[222:225], v[16:19]
	v_mfma_f32_16x16x32_bf16 v[12:15], v[176:179], v[230:233], v[12:15]
	v_mfma_f32_16x16x32_bf16 v[8:11], v[184:187], v[230:233], v[8:11]
	v_mfma_f32_16x16x32_bf16 v[4:7], v[176:179], v[238:241], v[4:7]
	v_mfma_f32_16x16x32_bf16 v[0:3], v[184:187], v[238:241], v[0:3]
	v_mfma_f32_16x16x32_bf16 v[28:31], v[180:183], v[196:199], v[28:31]
	v_mfma_f32_16x16x32_bf16 v[24:27], v[188:191], v[196:199], v[24:27]
	v_mfma_f32_16x16x32_bf16 v[20:23], v[180:183], v[226:229], v[20:23]
	v_mfma_f32_16x16x32_bf16 v[16:19], v[188:191], v[226:229], v[16:19]
	v_mfma_f32_16x16x32_bf16 v[12:15], v[180:183], v[234:237], v[12:15]
	v_mfma_f32_16x16x32_bf16 v[8:11], v[188:191], v[234:237], v[8:11]
	v_mfma_f32_16x16x32_bf16 v[4:7], v[180:183], v[242:245], v[4:7]
	v_mfma_f32_16x16x32_bf16 v[0:3], v[188:191], v[242:245], v[0:3]
	s_setprio 0
	s_barrier
; #define PG8_STAGE(bufoff, gbase, voff) do { _Pragma("unroll") for (int _i = 0; _i < 2; ++_i) \
;         __builtin_amdgcn_global_load_lds((const unsigned*)((const char*)(gbase) + (voff)[_i]), (PG8_LAS unsigned*)(lds + (bufoff) + ldsw + _i * 8192), 16, 0, 0); } while (0)
; #define PG8_LDA(dst, b, h) do { _Pragma("unroll") for (int m = 0; m < 4; ++m) _Pragma("unroll") for (int k = 0; k < 2; ++k) dst[m][k] = *(const PG8_LAS bf16x8*)(lds + PG8_SA(b, h) + aoff + m * 2048 + k * 1024); } while (0)
; #define PG8_LDB(dst, b, h) do { _Pragma("unroll") for (int n = 0; n < 2; ++n) _Pragma("unroll") for (int k = 0; k < 2; ++k) dst[n][k] = *(const PG8_LAS bf16x8*)(lds + PG8_SB(b, h) + boff + n * 2048 + k * 1024); } while (0)
; #define PG8_MMA(ai, bj, At, Bt) do { __builtin_amdgcn_s_setprio(1); _Pragma("unroll") for (int m = 0; m < 4; ++m) _Pragma("unroll") for (int n = 0; n < 2; ++n) _Pragma("unroll") for (int k = 0; k < 2; ++k) \
;         acc[ai][bj][m][n] = __builtin_amdgcn_mfma_f32_16x16x32_bf16(Bt[n][k], At[m][k], acc[ai][bj][m][n], 0, 0, 0); __builtin_amdgcn_s_setprio(0); } while (0)
; #define PG8_WAIT_V(n) asm volatile("s_waitcnt vmcnt(" #n ")" ::: "memory")
; #define PG8_WAIT_L(n) asm volatile("s_waitcnt lgkmcnt(" #n ")" ::: "memory")
; #define PG8_BAR __builtin_amdgcn_s_barrier()
; #define PG8_SCHED __builtin_amdgcn_sched_barrier(0)
; template <class Epi, class Sched, bool ALIGN_EPI = false, bool SP2 = false>
; __device__ __forceinline__ void gemm_phase(PG8_LAS unsigned char* lds, const Gemm g, const Sched& S, const Epi& E) {
;     ...
;             PG8_LDB(B0, 1, 0); PG8_LDB(B1, 1, 1); PG8_SCHED; PG8_LDA(At, 1, 0); PG8_STAGE(PG8_SA(0, 1), a2 + hstep, voffA);
;             PG8_WAIT_V(8); PG8_WAIT_L(0); PG8_BAR; PG8_MMA(0, 0, At, B0); PG8_MMA(0, 1, At, B1); PG8_BAR; PG8_SCHED;
;             PG8_LDA(At, 1, 1); PG8_STAGE(PG8_SB(1, 0), b3, voffB); PG8_STAGE(PG8_SB(1, 1), b3 + hstep, voffB); PG8_STAGE(PG8_SA(1, 0), a3, voffA);
;             PG8_WAIT_V(8); PG8_WAIT_L(0); PG8_BAR; PG8_MMA(1, 0, At, B0); PG8_MMA(1, 1, At, B1); PG8_BAR; PG8_SCHED;
;     ...
;         if constexpr (ALIGN_EPI) { if (wr == 0) PG8_BAR; }
	s_add_i32 s56, 0, 0x18000
	s_add_i32 s57, 0, 0x1c000
	ds_read_b128 v[154:157], v246 offset:32768
	ds_read_b128 v[164:167], v246 offset:33792
	ds_read_b128 v[168:171], v246 offset:34816
	ds_read_b128 v[172:175], v246 offset:35840
	ds_read_b128 v[176:179], v246 offset:49152
	ds_read_b128 v[180:183], v246 offset:50176
	ds_read_b128 v[184:187], v246 offset:51200
	ds_read_b128 v[188:191], v246 offset:52224
	s_add_u32 s52, s52, 0x80000
	s_addc_u32 s53, s53, 0
	s_mov_b32 m0, s12
	ds_read_b128 v[192:195], v145 offset:32768
	ds_read_b128 v[196:199], v145 offset:33792
	ds_read_b128 v[222:225], v145 offset:34816
	ds_read_b128 v[226:229], v145 offset:35840
	ds_read_b128 v[230:233], v145 offset:36864
	ds_read_b128 v[234:237], v145 offset:37888
	ds_read_b128 v[238:241], v145 offset:38912
	ds_read_b128 v[242:245], v145 offset:39936
	global_load_lds_dwordx4 v128, s[52:53]
	s_mov_b32 m0, s13
	s_nop 0
	global_load_lds_dwordx4 v132, s[52:53]
	s_waitcnt vmcnt(8)
	s_waitcnt lgkmcnt(0)
	s_barrier
	s_setprio 1
	v_mfma_f32_16x16x32_bf16 v[124:127], v[154:157], v[192:195], v[124:127]
	v_mfma_f32_16x16x32_bf16 v[120:123], v[168:171], v[192:195], v[120:123]
	v_mfma_f32_16x16x32_bf16 v[116:119], v[154:157], v[222:225], v[116:119]
	v_mfma_f32_16x16x32_bf16 v[112:115], v[168:171], v[222:225], v[112:115]
	v_mfma_f32_16x16x32_bf16 v[108:111], v[154:157], v[230:233], v[108:111]
	v_mfma_f32_16x16x32_bf16 v[104:107], v[168:171], v[230:233], v[104:107]
	v_mfma_f32_16x16x32_bf16 v[100:103], v[154:157], v[238:241], v[100:103]
	v_mfma_f32_16x16x32_bf16 v[96:99], v[168:171], v[238:241], v[96:99]
	v_mfma_f32_16x16x32_bf16 v[124:127], v[164:167], v[196:199], v[124:127]
	v_mfma_f32_16x16x32_bf16 v[120:123], v[172:175], v[196:199], v[120:123]
	v_mfma_f32_16x16x32_bf16 v[116:119], v[164:167], v[226:229], v[116:119]
	v_mfma_f32_16x16x32_bf16 v[112:115], v[172:175], v[226:229], v[112:115]
	v_mfma_f32_16x16x32_bf16 v[108:111], v[164:167], v[234:237], v[108:111]
	v_mfma_f32_16x16x32_bf16 v[104:107], v[172:175], v[234:237], v[104:107]
	v_mfma_f32_16x16x32_bf16 v[100:103], v[164:167], v[242:245], v[100:103]
	v_mfma_f32_16x16x32_bf16 v[96:99], v[172:175], v[242:245], v[96:99]
	v_mfma_f32_16x16x32_bf16 v[92:95], v[176:179], v[192:195], v[92:95]
	v_mfma_f32_16x16x32_bf16 v[88:91], v[184:187], v[192:195], v[88:91]
	v_mfma_f32_16x16x32_bf16 v[84:87], v[176:179], v[222:225], v[84:87]
	v_mfma_f32_16x16x32_bf16 v[80:83], v[184:187], v[222:225], v[80:83]
	v_mfma_f32_16x16x32_bf16 v[76:79], v[176:179], v[230:233], v[76:79]
	v_mfma_f32_16x16x32_bf16 v[72:75], v[184:187], v[230:233], v[72:75]
	v_mfma_f32_16x16x32_bf16 v[68:71], v[176:179], v[238:241], v[68:71]
	v_mfma_f32_16x16x32_bf16 v[64:67], v[184:187], v[238:241], v[64:67]
	v_mfma_f32_16x16x32_bf16 v[92:95], v[180:183], v[196:199], v[92:95]
	v_mfma_f32_16x16x32_bf16 v[88:91], v[188:191], v[196:199], v[88:91]
	v_mfma_f32_16x16x32_bf16 v[84:87], v[180:183], v[226:229], v[84:87]
	v_mfma_f32_16x16x32_bf16 v[80:83], v[188:191], v[226:229], v[80:83]
	v_mfma_f32_16x16x32_bf16 v[76:79], v[180:183], v[234:237], v[76:79]
	v_mfma_f32_16x16x32_bf16 v[72:75], v[188:191], v[234:237], v[72:75]
	v_mfma_f32_16x16x32_bf16 v[68:71], v[180:183], v[242:245], v[68:71]
	v_mfma_f32_16x16x32_bf16 v[64:67], v[188:191], v[242:245], v[64:67]
	s_setprio 0
	s_barrier
	s_add_i32 s52, s56, s63
	s_mov_b32 m0, s52
	ds_read_b128 v[192:195], v145 offset:49152
	ds_read_b128 v[196:199], v145 offset:50176
	ds_read_b128 v[222:225], v145 offset:51200
	ds_read_b128 v[226:229], v145 offset:52224
	ds_read_b128 v[230:233], v145 offset:53248
	ds_read_b128 v[234:237], v145 offset:54272
	ds_read_b128 v[238:241], v145 offset:55296
	ds_read_b128 v[242:245], v145 offset:56320
	s_add_u32 s4, s4, 0x80
	s_addc_u32 s5, s5, 0
	global_load_lds_dwordx4 v130, s[4:5]
	s_add_i32 m0, s52, 0x2000
	s_add_i32 s52, s57, s63
	global_load_lds_dwordx4 v134, s[4:5]
	s_add_u32 s4, s4, 0x80000
	s_addc_u32 s5, s5, 0
	s_mov_b32 m0, s52
	s_nop 0
	global_load_lds_dwordx4 v130, s[4:5]
	s_add_i32 m0, s52, 0x2000
	s_nop 0
	global_load_lds_dwordx4 v134, s[4:5]
	s_mov_b32 m0, s78
	s_nop 0
	global_load_lds_dwordx4 v128, s[98:99]
	s_mov_b32 m0, s79
	s_nop 0
	global_load_lds_dwordx4 v132, s[98:99]
	s_waitcnt vmcnt(8)
	s_waitcnt lgkmcnt(0)
	s_barrier
	s_setprio 1
	v_mfma_f32_16x16x32_bf16 v[60:63], v[154:157], v[192:195], v[60:63]
	v_mfma_f32_16x16x32_bf16 v[56:59], v[168:171], v[192:195], v[56:59]
	v_mfma_f32_16x16x32_bf16 v[52:55], v[154:157], v[222:225], v[52:55]
	v_mfma_f32_16x16x32_bf16 v[48:51], v[168:171], v[222:225], v[48:51]
	v_mfma_f32_16x16x32_bf16 v[44:47], v[154:157], v[230:233], v[44:47]
	v_mfma_f32_16x16x32_bf16 v[40:43], v[168:171], v[230:233], v[40:43]
	v_mfma_f32_16x16x32_bf16 v[36:39], v[154:157], v[238:241], v[36:39]
	v_mfma_f32_16x16x32_bf16 v[32:35], v[168:171], v[238:241], v[32:35]
	v_mfma_f32_16x16x32_bf16 v[60:63], v[164:167], v[196:199], v[60:63]
	v_mfma_f32_16x16x32_bf16 v[56:59], v[172:175], v[196:199], v[56:59]
	v_mfma_f32_16x16x32_bf16 v[52:55], v[164:167], v[226:229], v[52:55]
	v_mfma_f32_16x16x32_bf16 v[48:51], v[172:175], v[226:229], v[48:51]
	v_mfma_f32_16x16x32_bf16 v[44:47], v[164:167], v[234:237], v[44:47]
	v_mfma_f32_16x16x32_bf16 v[40:43], v[172:175], v[234:237], v[40:43]
	v_mfma_f32_16x16x32_bf16 v[36:39], v[164:167], v[242:245], v[36:39]
	v_mfma_f32_16x16x32_bf16 v[32:35], v[172:175], v[242:245], v[32:35]
	v_mfma_f32_16x16x32_bf16 v[28:31], v[176:179], v[192:195], v[28:31]
	v_mfma_f32_16x16x32_bf16 v[24:27], v[184:187], v[192:195], v[24:27]
	v_mfma_f32_16x16x32_bf16 v[20:23], v[176:179], v[222:225], v[20:23]
	v_mfma_f32_16x16x32_bf16 v[16:19], v[184:187], v[222:225], v[16:19]
	v_mfma_f32_16x16x32_bf16 v[12:15], v[176:179], v[230:233], v[12:15]
	v_mfma_f32_16x16x32_bf16 v[8:11], v[184:187], v[230:233], v[8:11]
	v_mfma_f32_16x16x32_bf16 v[4:7], v[176:179], v[238:241], v[4:7]
	v_mfma_f32_16x16x32_bf16 v[0:3], v[184:187], v[238:241], v[0:3]
	v_mfma_f32_16x16x32_bf16 v[28:31], v[180:183], v[196:199], v[28:31]
	v_mfma_f32_16x16x32_bf16 v[24:27], v[188:191], v[196:199], v[24:27]
	v_mfma_f32_16x16x32_bf16 v[20:23], v[180:183], v[226:229], v[20:23]
	v_mfma_f32_16x16x32_bf16 v[16:19], v[188:191], v[226:229], v[16:19]
	v_mfma_f32_16x16x32_bf16 v[12:15], v[180:183], v[234:237], v[12:15]
	v_mfma_f32_16x16x32_bf16 v[8:11], v[188:191], v[234:237], v[8:11]
	v_mfma_f32_16x16x32_bf16 v[4:7], v[180:183], v[242:245], v[4:7]
	v_mfma_f32_16x16x32_bf16 v[0:3], v[188:191], v[242:245], v[0:3]
	s_setprio 0
	s_barrier
	s_add_i32 s55, s55, 2
	s_add_u32 s14, s14, 0x100
	s_addc_u32 s15, s15, 0
	s_add_u32 s45, s45, 0x100
	s_addc_u32 s54, s54, 0
	s_cmp_gt_u32 s55, 29
	s_cbranch_scc0 .LBB0_322
	s_and_b64 vcc, exec, s[82:83]
	s_cbranch_vccz .LBB0_325
	s_barrier

; #define PG8_STAGE(bufoff, gbase, voff) do { _Pragma("unroll") for (int _i = 0; _i < 2; ++_i) \
;         __builtin_amdgcn_global_load_lds((const unsigned*)((const char*)(gbase) + (voff)[_i]), (PG8_LAS unsigned*)(lds + (bufoff) + ldsw + _i * 8192), 16, 0, 0); } while (0)
; #define PG8_LDA(dst, b, h) do { _Pragma("unroll") for (int m = 0; m < 4; ++m) _Pragma("unroll") for (int k = 0; k < 2; ++k) dst[m][k] = *(const PG8_LAS bf16x8*)(lds + PG8_SA(b, h) + aoff + m * 2048 + k * 1024); } while (0)
; #define PG8_LDB(dst, b, h) do { _Pragma("unroll") for (int n = 0; n < 2; ++n) _Pragma("unroll") for (int k = 0; k < 2; ++k) dst[n][k] = *(const PG8_LAS bf16x8*)(lds + PG8_SB(b, h) + boff + n * 2048 + k * 1024); } while (0)
; #define PG8_MMA(ai, bj, At, Bt) do { __builtin_amdgcn_s_setprio(1); _Pragma("unroll") for (int m = 0; m < 4; ++m) _Pragma("unroll") for (int n = 0; n < 2; ++n) _Pragma("unroll") for (int k = 0; k < 2; ++k) \
;         acc[ai][bj][m][n] = __builtin_amdgcn_mfma_f32_16x16x32_bf16(Bt[n][k], At[m][k], acc[ai][bj][m][n], 0, 0, 0); __builtin_amdgcn_s_setprio(0); } while (0)
; #define PG8_WAIT_V(n) asm volatile("s_waitcnt vmcnt(" #n ")" ::: "memory")
; #define PG8_WAIT_L(n) asm volatile("s_waitcnt lgkmcnt(" #n ")" ::: "memory")
; template <class Epi, class Sched, bool ALIGN_EPI = false, bool SP2 = false>
; __device__ __forceinline__ void gemm_phase(PG8_LAS unsigned char* lds, const Gemm g, const Sched& S, const Epi& E) {
;     ...
;             const bool last = (t == nt - 2);
;             const char* a1 = cA + (size_t)(t + 1) * kstep;
;             const char* a2 = last ? nA : cA + (size_t)(t + 2) * kstep; const char* b2 = last ? nB : cB + (size_t)(t + 2) * kstep;
;             const char* a3 = a2 + kstep; const char* b3 = b2 + kstep;
;             if (last && has_next) S.a_ready(nxt);
;             if constexpr (SP2) {
;             PG8_LDB(B0, 0, 0); PG8_LDB(B1, 0, 1); PG8_SCHED; PG8_LDA(At, 0, 0); PG8_STAGE(PG8_SA(1, 1), a1 + hstep, voffA);
;             PG8_WAIT_V(8); PG8_WAIT_L(0); PG8_BAR; PG8_MMA(0, 0, At, B0); PG8_MMA(0, 1, At, B1); PG8_BAR; PG8_SCHED;
;             PG8_LDA(At, 0, 1); PG8_STAGE(PG8_SB(0, 0), b2, voffB); PG8_STAGE(PG8_SB(0, 1), b2 + hstep, voffB); PG8_STAGE(PG8_SA(0, 0), a2, voffA);
;             PG8_WAIT_V(8); PG8_WAIT_L(0); PG8_BAR; PG8_MMA(1, 0, At, B0); PG8_MMA(1, 1, At, B1); PG8_BAR; PG8_SCHED;
.LBB0_849:
	s_add_i32 s76, 0, 0x10000
	s_add_i32 s78, 0, 0x14000
	ds_read_b128 v[144:147], v200
	ds_read_b128 v[148:151], v200 offset:1024
	ds_read_b128 v[152:155], v200 offset:2048
	ds_read_b128 v[156:159], v200 offset:3072
	ds_read_b128 v[164:167], v200 offset:16384
	ds_read_b128 v[168:171], v200 offset:17408
	ds_read_b128 v[172:175], v200 offset:18432
	ds_read_b128 v[176:179], v200 offset:19456
	s_add_i32 m0, s51, 0xc000
	ds_read_b128 v[180:183], v143
	ds_read_b128 v[184:187], v143 offset:1024
	ds_read_b128 v[188:191], v143 offset:2048
	ds_read_b128 v[192:195], v143 offset:3072
	ds_read_b128 v[196:199], v143 offset:4096
	ds_read_b128 v[222:225], v143 offset:5120
	ds_read_b128 v[226:229], v143 offset:6144
	ds_read_b128 v[230:233], v143 offset:7168
	global_load_lds_dwordx4 v134, s[70:71]
	s_add_i32 m0, s51, 0xe000
	s_nop 0
	global_load_lds_dwordx4 v136, s[70:71]
	s_add_u32 s4, s70, 0xfff80080
	s_addc_u32 s5, s71, -1
	s_cmp_eq_u32 s75, 28
	s_cselect_b32 s53, s11, s5
	s_cselect_b32 s52, s63, s4
	s_cselect_b32 s5, s13, s74
	s_cselect_b32 s4, s72, s73
	s_waitcnt vmcnt(8)
	s_waitcnt lgkmcnt(0)
	s_barrier
	s_setprio 1
	v_mfma_f32_16x16x32_bf16 v[124:127], v[144:147], v[180:183], v[124:127]
	v_mfma_f32_16x16x32_bf16 v[116:119], v[152:155], v[180:183], v[116:119]
	v_mfma_f32_16x16x32_bf16 v[108:111], v[144:147], v[188:191], v[108:111]
	v_mfma_f32_16x16x32_bf16 v[100:103], v[152:155], v[188:191], v[100:103]
	v_mfma_f32_16x16x32_bf16 v[92:95], v[144:147], v[196:199], v[92:95]
	v_mfma_f32_16x16x32_bf16 v[84:87], v[152:155], v[196:199], v[84:87]
	v_mfma_f32_16x16x32_bf16 v[76:79], v[144:147], v[226:229], v[76:79]
	v_mfma_f32_16x16x32_bf16 v[68:71], v[152:155], v[226:229], v[68:71]
	v_mfma_f32_16x16x32_bf16 v[124:127], v[148:151], v[184:187], v[124:127]
	v_mfma_f32_16x16x32_bf16 v[116:119], v[156:159], v[184:187], v[116:119]
	v_mfma_f32_16x16x32_bf16 v[108:111], v[148:151], v[192:195], v[108:111]
	v_mfma_f32_16x16x32_bf16 v[100:103], v[156:159], v[192:195], v[100:103]
	v_mfma_f32_16x16x32_bf16 v[92:95], v[148:151], v[222:225], v[92:95]
	v_mfma_f32_16x16x32_bf16 v[84:87], v[156:159], v[222:225], v[84:87]
	v_mfma_f32_16x16x32_bf16 v[76:79], v[148:151], v[230:233], v[76:79]
	v_mfma_f32_16x16x32_bf16 v[68:71], v[156:159], v[230:233], v[68:71]
	v_mfma_f32_16x16x32_bf16 v[120:123], v[164:167], v[180:183], v[120:123]
	v_mfma_f32_16x16x32_bf16 v[112:115], v[172:175], v[180:183], v[112:115]
	v_mfma_f32_16x16x32_bf16 v[104:107], v[164:167], v[188:191], v[104:107]
	v_mfma_f32_16x16x32_bf16 v[96:99], v[172:175], v[188:191], v[96:99]
	v_mfma_f32_16x16x32_bf16 v[88:91], v[164:167], v[196:199], v[88:91]
	v_mfma_f32_16x16x32_bf16 v[80:83], v[172:175], v[196:199], v[80:83]
	v_mfma_f32_16x16x32_bf16 v[72:75], v[164:167], v[226:229], v[72:75]
	v_mfma_f32_16x16x32_bf16 v[64:67], v[172:175], v[226:229], v[64:67]
	v_mfma_f32_16x16x32_bf16 v[120:123], v[168:171], v[184:187], v[120:123]
	v_mfma_f32_16x16x32_bf16 v[112:115], v[176:179], v[184:187], v[112:115]
	v_mfma_f32_16x16x32_bf16 v[104:107], v[168:171], v[192:195], v[104:107]
	v_mfma_f32_16x16x32_bf16 v[96:99], v[176:179], v[192:195], v[96:99]
	v_mfma_f32_16x16x32_bf16 v[88:91], v[168:171], v[222:225], v[88:91]
	v_mfma_f32_16x16x32_bf16 v[80:83], v[176:179], v[222:225], v[80:83]
	v_mfma_f32_16x16x32_bf16 v[72:75], v[168:171], v[230:233], v[72:75]
	v_mfma_f32_16x16x32_bf16 v[64:67], v[176:179], v[230:233], v[64:67]
	s_setprio 0
	s_barrier
	s_add_i32 s76, s76, s24
	s_mov_b32 m0, s76
	ds_read_b128 v[180:183], v143 offset:16384
	ds_read_b128 v[184:187], v143 offset:17408
	ds_read_b128 v[188:191], v143 offset:18432
	ds_read_b128 v[192:195], v143 offset:19456
	ds_read_b128 v[196:199], v143 offset:20480
	ds_read_b128 v[222:225], v143 offset:21504
	ds_read_b128 v[226:229], v143 offset:22528
	ds_read_b128 v[230:233], v143 offset:23552
	global_load_lds_dwordx4 v160, s[4:5]
	s_add_i32 m0, s76, 0x2000
	s_add_u32 s76, s4, 0x80000
	s_addc_u32 s77, s5, 0
	s_add_i32 s78, s78, s24
	global_load_lds_dwordx4 v128, s[4:5]
	s_mov_b32 m0, s78
	s_nop 0
	global_load_lds_dwordx4 v160, s[76:77]
	s_add_i32 m0, s78, 0x2000
	s_nop 0
	global_load_lds_dwordx4 v128, s[76:77]
	s_mov_b32 m0, s51
	s_nop 0
	global_load_lds_dwordx4 v132, s[52:53]
	s_mov_b32 m0, s55
	s_nop 0
	global_load_lds_dwordx4 v130, s[52:53]
	s_add_u32 s98, s52, 0x80
	s_addc_u32 s99, s53, 0
	s_waitcnt vmcnt(8)
	s_waitcnt lgkmcnt(0)
	s_barrier
	s_setprio 1
	v_mfma_f32_16x16x32_bf16 v[60:63], v[144:147], v[180:183], v[60:63]
	v_mfma_f32_16x16x32_bf16 v[52:55], v[152:155], v[180:183], v[52:55]
	v_mfma_f32_16x16x32_bf16 v[44:47], v[144:147], v[188:191], v[44:47]
	v_mfma_f32_16x16x32_bf16 v[36:39], v[152:155], v[188:191], v[36:39]
	v_mfma_f32_16x16x32_bf16 v[28:31], v[144:147], v[196:199], v[28:31]
	v_mfma_f32_16x16x32_bf16 v[20:23], v[152:155], v[196:199], v[20:23]
	v_mfma_f32_16x16x32_bf16 v[12:15], v[144:147], v[226:229], v[12:15]
	v_mfma_f32_16x16x32_bf16 v[4:7], v[152:155], v[226:229], v[4:7]
	v_mfma_f32_16x16x32_bf16 v[60:63], v[148:151], v[184:187], v[60:63]
	v_mfma_f32_16x16x32_bf16 v[52:55], v[156:159], v[184:187], v[52:55]
	v_mfma_f32_16x16x32_bf16 v[44:47], v[148:151], v[192:195], v[44:47]
	v_mfma_f32_16x16x32_bf16 v[36:39], v[156:159], v[192:195], v[36:39]
	v_mfma_f32_16x16x32_bf16 v[28:31], v[148:151], v[222:225], v[28:31]
	v_mfma_f32_16x16x32_bf16 v[20:23], v[156:159], v[222:225], v[20:23]
	v_mfma_f32_16x16x32_bf16 v[12:15], v[148:151], v[230:233], v[12:15]
	v_mfma_f32_16x16x32_bf16 v[4:7], v[156:159], v[230:233], v[4:7]
	v_mfma_f32_16x16x32_bf16 v[56:59], v[164:167], v[180:183], v[56:59]
	v_mfma_f32_16x16x32_bf16 v[48:51], v[172:175], v[180:183], v[48:51]
	v_mfma_f32_16x16x32_bf16 v[40:43], v[164:167], v[188:191], v[40:43]
	v_mfma_f32_16x16x32_bf16 v[32:35], v[172:175], v[188:191], v[32:35]
	v_mfma_f32_16x16x32_bf16 v[24:27], v[164:167], v[196:199], v[24:27]
	v_mfma_f32_16x16x32_bf16 v[16:19], v[172:175], v[196:199], v[16:19]
	v_mfma_f32_16x16x32_bf16 v[8:11], v[164:167], v[226:229], v[8:11]
	v_mfma_f32_16x16x32_bf16 v[0:3], v[172:175], v[226:229], v[0:3]
	v_mfma_f32_16x16x32_bf16 v[56:59], v[168:171], v[184:187], v[56:59]
	v_mfma_f32_16x16x32_bf16 v[48:51], v[176:179], v[184:187], v[48:51]
	v_mfma_f32_16x16x32_bf16 v[40:43], v[168:171], v[192:195], v[40:43]
	v_mfma_f32_16x16x32_bf16 v[32:35], v[176:179], v[192:195], v[32:35]
	v_mfma_f32_16x16x32_bf16 v[24:27], v[168:171], v[222:225], v[24:27]
	v_mfma_f32_16x16x32_bf16 v[16:19], v[176:179], v[222:225], v[16:19]
	v_mfma_f32_16x16x32_bf16 v[8:11], v[168:171], v[230:233], v[8:11]
	v_mfma_f32_16x16x32_bf16 v[0:3], v[176:179], v[230:233], v[0:3]
	s_setprio 0
	s_barrier
; #define PG8_STAGE(bufoff, gbase, voff) do { _Pragma("unroll") for (int _i = 0; _i < 2; ++_i) \
;         __builtin_amdgcn_global_load_lds((const unsigned*)((const char*)(gbase) + (voff)[_i]), (PG8_LAS unsigned*)(lds + (bufoff) + ldsw + _i * 8192), 16, 0, 0); } while (0)
; #define PG8_LDA(dst, b, h) do { _Pragma("unroll") for (int m = 0; m < 4; ++m) _Pragma("unroll") for (int k = 0; k < 2; ++k) dst[m][k] = *(const PG8_LAS bf16x8*)(lds + PG8_SA(b, h) + aoff + m * 2048 + k * 1024); } while (0)
; #define PG8_LDB(dst, b, h) do { _Pragma("unroll") for (int n = 0; n < 2; ++n) _Pragma("unroll") for (int k = 0; k < 2; ++k) dst[n][k] = *(const PG8_LAS bf16x8*)(lds + PG8_SB(b, h) + boff + n * 2048 + k * 1024); } while (0)
; #define PG8_MMA(ai, bj, At, Bt) do { __builtin_amdgcn_s_setprio(1); _Pragma("unroll") for (int m = 0; m < 4; ++m) _Pragma("unroll") for (int n = 0; n < 2; ++n) _Pragma("unroll") for (int k = 0; k < 2; ++k) \
;         acc[ai][bj][m][n] = __builtin_amdgcn_mfma_f32_16x16x32_bf16(Bt[n][k], At[m][k], acc[ai][bj][m][n], 0, 0, 0); __builtin_amdgcn_s_setprio(0); } while (0)
; #define PG8_WAIT_V(n) asm volatile("s_waitcnt vmcnt(" #n ")" ::: "memory")
; #define PG8_WAIT_L(n) asm volatile("s_waitcnt lgkmcnt(" #n ")" ::: "memory")
; #define PG8_BAR __builtin_amdgcn_s_barrier()
; #define PG8_SCHED __builtin_amdgcn_sched_barrier(0)
; template <class Epi, class Sched, bool ALIGN_EPI = false, bool SP2 = false>
; __device__ __forceinline__ void gemm_phase(PG8_LAS unsigned char* lds, const Gemm g, const Sched& S, const Epi& E) {
;     ...
;             PG8_LDB(B0, 1, 0); PG8_LDB(B1, 1, 1); PG8_SCHED; PG8_LDA(At, 1, 0); PG8_STAGE(PG8_SA(0, 1), a2 + hstep, voffA);
;             PG8_WAIT_V(8); PG8_WAIT_L(0); PG8_BAR; PG8_MMA(0, 0, At, B0); PG8_MMA(0, 1, At, B1); PG8_BAR; PG8_SCHED;
;             PG8_LDA(At, 1, 1); PG8_STAGE(PG8_SB(1, 0), b3, voffB); PG8_STAGE(PG8_SB(1, 1), b3 + hstep, voffB); PG8_STAGE(PG8_SA(1, 0), a3, voffA);
;             PG8_WAIT_V(8); PG8_WAIT_L(0); PG8_BAR; PG8_MMA(1, 0, At, B0); PG8_MMA(1, 1, At, B1); PG8_BAR; PG8_SCHED;
;     ...
;         if constexpr (ALIGN_EPI) { if (wr == 0) PG8_BAR; }
	s_add_i32 s76, 0, 0x18000
	s_add_i32 s77, 0, 0x1c000
	ds_read_b128 v[144:147], v200 offset:32768
	ds_read_b128 v[148:151], v200 offset:33792
	ds_read_b128 v[152:155], v200 offset:34816
	ds_read_b128 v[156:159], v200 offset:35840
	ds_read_b128 v[164:167], v200 offset:49152
	ds_read_b128 v[168:171], v200 offset:50176
	ds_read_b128 v[172:175], v200 offset:51200
	ds_read_b128 v[176:179], v200 offset:52224
	s_add_u32 s52, s52, 0x80000
	s_addc_u32 s53, s53, 0
	s_mov_b32 m0, s56
	ds_read_b128 v[180:183], v143 offset:32768
	ds_read_b128 v[184:187], v143 offset:33792
	ds_read_b128 v[188:191], v143 offset:34816
	ds_read_b128 v[192:195], v143 offset:35840
	ds_read_b128 v[196:199], v143 offset:36864
	ds_read_b128 v[222:225], v143 offset:37888
	ds_read_b128 v[226:229], v143 offset:38912
	ds_read_b128 v[230:233], v143 offset:39936
	global_load_lds_dwordx4 v132, s[52:53]
	s_mov_b32 m0, s57
	s_nop 0
	global_load_lds_dwordx4 v130, s[52:53]
	s_waitcnt vmcnt(8)
	s_waitcnt lgkmcnt(0)
	s_barrier
	s_setprio 1
	v_mfma_f32_16x16x32_bf16 v[124:127], v[144:147], v[180:183], v[124:127]
	v_mfma_f32_16x16x32_bf16 v[116:119], v[152:155], v[180:183], v[116:119]
	v_mfma_f32_16x16x32_bf16 v[108:111], v[144:147], v[188:191], v[108:111]
	v_mfma_f32_16x16x32_bf16 v[100:103], v[152:155], v[188:191], v[100:103]
	v_mfma_f32_16x16x32_bf16 v[92:95], v[144:147], v[196:199], v[92:95]
	v_mfma_f32_16x16x32_bf16 v[84:87], v[152:155], v[196:199], v[84:87]
	v_mfma_f32_16x16x32_bf16 v[76:79], v[144:147], v[226:229], v[76:79]
	v_mfma_f32_16x16x32_bf16 v[68:71], v[152:155], v[226:229], v[68:71]
	v_mfma_f32_16x16x32_bf16 v[124:127], v[148:151], v[184:187], v[124:127]
	v_mfma_f32_16x16x32_bf16 v[116:119], v[156:159], v[184:187], v[116:119]
	v_mfma_f32_16x16x32_bf16 v[108:111], v[148:151], v[192:195], v[108:111]
	v_mfma_f32_16x16x32_bf16 v[100:103], v[156:159], v[192:195], v[100:103]
	v_mfma_f32_16x16x32_bf16 v[92:95], v[148:151], v[222:225], v[92:95]
	v_mfma_f32_16x16x32_bf16 v[84:87], v[156:159], v[222:225], v[84:87]
	v_mfma_f32_16x16x32_bf16 v[76:79], v[148:151], v[230:233], v[76:79]
	v_mfma_f32_16x16x32_bf16 v[68:71], v[156:159], v[230:233], v[68:71]
	v_mfma_f32_16x16x32_bf16 v[120:123], v[164:167], v[180:183], v[120:123]
	v_mfma_f32_16x16x32_bf16 v[112:115], v[172:175], v[180:183], v[112:115]
	v_mfma_f32_16x16x32_bf16 v[104:107], v[164:167], v[188:191], v[104:107]
	v_mfma_f32_16x16x32_bf16 v[96:99], v[172:175], v[188:191], v[96:99]
	v_mfma_f32_16x16x32_bf16 v[88:91], v[164:167], v[196:199], v[88:91]
	v_mfma_f32_16x16x32_bf16 v[80:83], v[172:175], v[196:199], v[80:83]
	v_mfma_f32_16x16x32_bf16 v[72:75], v[164:167], v[226:229], v[72:75]
	v_mfma_f32_16x16x32_bf16 v[64:67], v[172:175], v[226:229], v[64:67]
	v_mfma_f32_16x16x32_bf16 v[120:123], v[168:171], v[184:187], v[120:123]
	v_mfma_f32_16x16x32_bf16 v[112:115], v[176:179], v[184:187], v[112:115]
	v_mfma_f32_16x16x32_bf16 v[104:107], v[168:171], v[192:195], v[104:107]
	v_mfma_f32_16x16x32_bf16 v[96:99], v[176:179], v[192:195], v[96:99]
	v_mfma_f32_16x16x32_bf16 v[88:91], v[168:171], v[222:225], v[88:91]
	v_mfma_f32_16x16x32_bf16 v[80:83], v[176:179], v[222:225], v[80:83]
	v_mfma_f32_16x16x32_bf16 v[72:75], v[168:171], v[230:233], v[72:75]
	v_mfma_f32_16x16x32_bf16 v[64:67], v[176:179], v[230:233], v[64:67]
	s_setprio 0
	s_barrier
	s_add_i32 s52, s76, s24
	s_mov_b32 m0, s52
	ds_read_b128 v[180:183], v143 offset:49152
	ds_read_b128 v[184:187], v143 offset:50176
	ds_read_b128 v[188:191], v143 offset:51200
	ds_read_b128 v[192:195], v143 offset:52224
	ds_read_b128 v[196:199], v143 offset:53248
	ds_read_b128 v[222:225], v143 offset:54272
	ds_read_b128 v[226:229], v143 offset:55296
	ds_read_b128 v[230:233], v143 offset:56320
	s_add_u32 s4, s4, 0x80
	s_addc_u32 s5, s5, 0
	global_load_lds_dwordx4 v160, s[4:5]
	s_add_i32 m0, s52, 0x2000
	s_add_i32 s52, s77, s24
	global_load_lds_dwordx4 v128, s[4:5]
	s_add_u32 s4, s4, 0x80000
	s_addc_u32 s5, s5, 0
	s_mov_b32 m0, s52
	s_nop 0
	global_load_lds_dwordx4 v160, s[4:5]
	s_add_i32 m0, s52, 0x2000
	s_nop 0
	global_load_lds_dwordx4 v128, s[4:5]
	s_mov_b32 m0, s58
	s_nop 0
	global_load_lds_dwordx4 v132, s[98:99]
	s_mov_b32 m0, s59
	s_nop 0
	global_load_lds_dwordx4 v130, s[98:99]
	s_waitcnt vmcnt(8)
	s_waitcnt lgkmcnt(0)
	s_barrier
	s_setprio 1
	v_mfma_f32_16x16x32_bf16 v[60:63], v[144:147], v[180:183], v[60:63]
	v_mfma_f32_16x16x32_bf16 v[52:55], v[152:155], v[180:183], v[52:55]
	v_mfma_f32_16x16x32_bf16 v[44:47], v[144:147], v[188:191], v[44:47]
	v_mfma_f32_16x16x32_bf16 v[36:39], v[152:155], v[188:191], v[36:39]
	v_mfma_f32_16x16x32_bf16 v[28:31], v[144:147], v[196:199], v[28:31]
	v_mfma_f32_16x16x32_bf16 v[20:23], v[152:155], v[196:199], v[20:23]
	v_mfma_f32_16x16x32_bf16 v[12:15], v[144:147], v[226:229], v[12:15]
	v_mfma_f32_16x16x32_bf16 v[4:7], v[152:155], v[226:229], v[4:7]
	v_mfma_f32_16x16x32_bf16 v[60:63], v[148:151], v[184:187], v[60:63]
	v_mfma_f32_16x16x32_bf16 v[52:55], v[156:159], v[184:187], v[52:55]
	v_mfma_f32_16x16x32_bf16 v[44:47], v[148:151], v[192:195], v[44:47]
	v_mfma_f32_16x16x32_bf16 v[36:39], v[156:159], v[192:195], v[36:39]
	v_mfma_f32_16x16x32_bf16 v[28:31], v[148:151], v[222:225], v[28:31]
	v_mfma_f32_16x16x32_bf16 v[20:23], v[156:159], v[222:225], v[20:23]
	v_mfma_f32_16x16x32_bf16 v[12:15], v[148:151], v[230:233], v[12:15]
	v_mfma_f32_16x16x32_bf16 v[4:7], v[156:159], v[230:233], v[4:7]
	v_mfma_f32_16x16x32_bf16 v[56:59], v[164:167], v[180:183], v[56:59]
	v_mfma_f32_16x16x32_bf16 v[48:51], v[172:175], v[180:183], v[48:51]
	v_mfma_f32_16x16x32_bf16 v[40:43], v[164:167], v[188:191], v[40:43]
	v_mfma_f32_16x16x32_bf16 v[32:35], v[172:175], v[188:191], v[32:35]
	v_mfma_f32_16x16x32_bf16 v[24:27], v[164:167], v[196:199], v[24:27]
	v_mfma_f32_16x16x32_bf16 v[16:19], v[172:175], v[196:199], v[16:19]
	v_mfma_f32_16x16x32_bf16 v[8:11], v[164:167], v[226:229], v[8:11]
	v_mfma_f32_16x16x32_bf16 v[0:3], v[172:175], v[226:229], v[0:3]
	v_mfma_f32_16x16x32_bf16 v[56:59], v[168:171], v[184:187], v[56:59]
	v_mfma_f32_16x16x32_bf16 v[48:51], v[176:179], v[184:187], v[48:51]
	v_mfma_f32_16x16x32_bf16 v[40:43], v[168:171], v[192:195], v[40:43]
	v_mfma_f32_16x16x32_bf16 v[32:35], v[176:179], v[192:195], v[32:35]
	v_mfma_f32_16x16x32_bf16 v[24:27], v[168:171], v[222:225], v[24:27]
	v_mfma_f32_16x16x32_bf16 v[16:19], v[176:179], v[222:225], v[16:19]
	v_mfma_f32_16x16x32_bf16 v[8:11], v[168:171], v[230:233], v[8:11]
	v_mfma_f32_16x16x32_bf16 v[0:3], v[176:179], v[230:233], v[0:3]
	s_setprio 0
	s_barrier
	s_add_i32 s75, s75, 2
	s_add_u32 s70, s70, 0x100
	s_addc_u32 s71, s71, 0
	s_add_u32 s73, s73, 0x100
	s_addc_u32 s74, s74, 0
	s_cmp_gt_u32 s75, 29
	s_cbranch_scc0 .LBB0_849
	s_and_b64 vcc, exec, s[8:9]
	s_cbranch_vccz .LBB0_852
	s_barrier
